# speedup vs baseline: 1.0116x; 1.0116x over previous
; __device__ __forceinline__ unsigned cvt_pk_bf16(float lo, float hi) { unsigned r; asm volatile("v_cvt_pk_bf16_f32 %0, %1, %2" : "=v"(r) : "v"(lo), "v"(hi)); return r; }
; __device__ __forceinline__ f32x4 gelu4(const f32x4 x) {
;     const f32x4 t = x * x, a = x * (t * -0.10294324f + -2.3022082f);
;     f32x4 e; e[0] = __builtin_amdgcn_exp2f(a[0]); e[1] = __builtin_amdgcn_exp2f(a[1]); e[2] = __builtin_amdgcn_exp2f(a[2]); e[3] = __builtin_amdgcn_exp2f(a[3]);
;     const f32x4 d = e + 1.0f;
;     f32x4 r; r[0] = __builtin_amdgcn_rcpf(d[0]); r[1] = __builtin_amdgcn_rcpf(d[1]); r[2] = __builtin_amdgcn_rcpf(d[2]); r[3] = __builtin_amdgcn_rcpf(d[3]);
;     return x * r;
; }
;     __device__ __forceinline__ void operator()(const f32x4 (&acc)[2][2][4][2], const Unit& u, int wr, int wc, int fr, int fq) const {
;         const int row0 = u.pm * BM + wr * 64 + fr, col0 = u.pn * BM + wc * 32 + 4 * fq;
;         const bool act = (u.pn >= 2) && (u.pn < 10), st = (u.pn >= 6) && (u.pn < 10);
; #pragma unroll
;         for (int ai = 0; ai < 2; ++ai)
; #pragma unroll
;             for (int m = 0; m < 4; ++m) {
;                 const int row = row0 + ai * HALF + m * 16; bf16_t* rowp = proj + (size_t)row * INW + col0; float s = 0.f, q = 0.f;
; #pragma unroll
;                 for (int bj = 0; bj < 2; ++bj)
; #pragma unroll
;                     for (int n = 0; n < 2; ++n) { f32x4 v = acc[ai][bj][m][n];
;                         if (act) v = gelu4(v);
;                         s += (v[0] + v[1]) + (v[2] + v[3]); q += (v[0] * v[0] + v[1] * v[1]) + (v[2] * v[2] + v[3] * v[3]);
;                         u32x2 pk; pk.x = cvt_pk_bf16(v[0], v[1]); pk.y = cvt_pk_bf16(v[2], v[3]); *(u32x2*)(rowp + bj * HALF + n * 16) = pk; }
;                 if (st) { s += __shfl_xor(s, 16); s += __shfl_xor(s, 32); q += __shfl_xor(q, 16); q += __shfl_xor(q, 32);
;                     if (fq == 0) { float* sp = stats + ((size_t)row * 16 + (u.pn - 6) * 4 + wc) * 2; sp[0] = s; sp[1] = q; } }
.LBB0_1278:
	v_bfe_u32 v156, v200, 4, 1
	v_mul_u32_u24_e32 v156, 24, v156
	v_mov_b32_e32 v157, 0
	v_lshlrev_b32_e32 v64, 2, v136
	v_lshl_add_u32 v130, s13, 8, v137
	v_lshl_or_b32 v64, s12, 5, v64
	v_ashrrev_i32_e32 v131, 31, v130
	v_lshl_or_b32 v64, s11, 8, v64
	v_lshlrev_b64 v[132:133], 13, v[130:131]
	v_lshl_add_u64 v[132:133], s[80:81], 0, v[132:133]
	v_lshlrev_b32_e32 v64, 1, v64
	v_lshl_add_u64 v[132:133], v[132:133], 0, v[64:65]
	v_cvt_pk_bf16_f32 v152, v126, v127
	v_cvt_pk_bf16_f32 v153, v128, v129
	v_cndmask_b32_e64 v134, 0, 1, s[2:3]
	v_cmp_ne_u32_e64 s[0:1], 1, v134
	s_andn2_b64 vcc, exec, s[2:3]
	s_cbranch_vccnz .LBB0_1280
	s_mov_b32 s2, 0xc0135761
	v_pk_mul_f32 v[134:135], v[124:125], v[124:125]
	v_pk_mul_f32 v[138:139], v[122:123], v[122:123]
	v_mov_b64_e32 v[140:141], s[2:3]
	s_mov_b32 s2, 0xbdd2d3e8
	v_pk_fma_f32 v[134:135], v[134:135], s[2:3], v[140:141] op_sel_hi:[1,0,0]
	v_pk_fma_f32 v[138:139], v[138:139], s[2:3], v[140:141] op_sel_hi:[1,0,0]
	v_pk_mul_f32 v[134:135], v[124:125], v[134:135]
	v_pk_mul_f32 v[138:139], v[122:123], v[138:139]
	v_exp_f32_e32 v134, v134
	v_exp_f32_e32 v138, v138
	v_exp_f32_e32 v135, v135
	v_exp_f32_e32 v139, v139
	v_pk_add_f32 v[134:135], v[134:135], 1.0 op_sel_hi:[1,0]
	v_pk_add_f32 v[138:139], v[138:139], 1.0 op_sel_hi:[1,0]
	v_rcp_f32_e32 v134, v134
	v_rcp_f32_e32 v138, v138
	v_rcp_f32_e32 v135, v135
	v_rcp_f32_e32 v139, v139
	v_pk_mul_f32 v[124:125], v[124:125], v[134:135]
	v_pk_mul_f32 v[122:123], v[122:123], v[138:139]
.LBB0_1280:
	v_readlane_b32 s24, v251, 38
	v_readlane_b32 s25, v251, 39
	s_and_b64 vcc, exec, s[0:1]
	v_cvt_pk_bf16_f32 v154, v122, v123
	v_cvt_pk_bf16_f32 v155, v124, v125
	s_nop 1
	v_permlane16_swap_b32_e32 v152, v154
	v_permlane16_swap_b32_e32 v153, v155
	v_lshl_add_u64 v[158:159], v[132:133], 0, v[156:157]
	global_store_dwordx4 v[158:159], v[152:155], off
	s_nop 1
	s_cbranch_vccnz .LBB0_1282
	s_mov_b32 s2, 0xc0135761
	v_pk_mul_f32 v[134:135], v[120:121], v[120:121]
	v_pk_mul_f32 v[138:139], v[118:119], v[118:119]
	v_mov_b64_e32 v[140:141], s[2:3]
	s_mov_b32 s2, 0xbdd2d3e8
	v_pk_fma_f32 v[134:135], v[134:135], s[2:3], v[140:141] op_sel_hi:[1,0,0]
	v_pk_fma_f32 v[138:139], v[138:139], s[2:3], v[140:141] op_sel_hi:[1,0,0]
	v_pk_mul_f32 v[134:135], v[120:121], v[134:135]
	v_pk_mul_f32 v[138:139], v[118:119], v[138:139]
	v_exp_f32_e32 v134, v134
	v_exp_f32_e32 v138, v138
	v_exp_f32_e32 v135, v135
	v_exp_f32_e32 v139, v139
	v_pk_add_f32 v[134:135], v[134:135], 1.0 op_sel_hi:[1,0]
	v_pk_add_f32 v[138:139], v[138:139], 1.0 op_sel_hi:[1,0]
	v_rcp_f32_e32 v134, v134
	v_rcp_f32_e32 v138, v138
	v_rcp_f32_e32 v135, v135
	v_rcp_f32_e32 v139, v139
	v_pk_mul_f32 v[120:121], v[120:121], v[134:135]
	v_pk_mul_f32 v[118:119], v[118:119], v[138:139]
.LBB0_1282:
	s_and_b64 vcc, exec, s[0:1]
	v_cvt_pk_bf16_f32 v152, v118, v119
	v_cvt_pk_bf16_f32 v153, v120, v121
	s_cbranch_vccnz .LBB0_1284
	s_mov_b32 s2, 0xc0135761
	v_pk_mul_f32 v[134:135], v[116:117], v[116:117]
	v_pk_mul_f32 v[138:139], v[114:115], v[114:115]
	v_mov_b64_e32 v[140:141], s[2:3]
	s_mov_b32 s2, 0xbdd2d3e8
	v_pk_fma_f32 v[134:135], v[134:135], s[2:3], v[140:141] op_sel_hi:[1,0,0]
	v_pk_fma_f32 v[138:139], v[138:139], s[2:3], v[140:141] op_sel_hi:[1,0,0]
	v_pk_mul_f32 v[134:135], v[116:117], v[134:135]
	v_pk_mul_f32 v[138:139], v[114:115], v[138:139]
	v_exp_f32_e32 v134, v134
	v_exp_f32_e32 v138, v138
	v_exp_f32_e32 v135, v135
	v_exp_f32_e32 v139, v139
	v_pk_add_f32 v[134:135], v[134:135], 1.0 op_sel_hi:[1,0]
	v_pk_add_f32 v[138:139], v[138:139], 1.0 op_sel_hi:[1,0]
	v_rcp_f32_e32 v134, v134
	v_rcp_f32_e32 v138, v138
	v_rcp_f32_e32 v135, v135
	v_rcp_f32_e32 v139, v139
	v_pk_mul_f32 v[116:117], v[116:117], v[134:135]
	v_pk_mul_f32 v[114:115], v[114:115], v[138:139]
.LBB0_1284:
	s_add_i32 s2, s11, -6
	s_cmp_lt_u32 s2, 4
	s_cselect_b64 s[8:9], -1, 0
	s_lshl_b32 s3, s11, 2
	s_or_b32 s3, s3, s12
	s_sub_i32 s94, s3, 24
	v_cmp_eq_u32_e64 s[6:7], 0, v136
	s_cmp_gt_u32 s2, 3
	v_cvt_pk_bf16_f32 v154, v114, v115
	v_cvt_pk_bf16_f32 v155, v116, v117
	s_nop 1
	v_permlane16_swap_b32_e32 v152, v154
	v_permlane16_swap_b32_e32 v153, v155
	v_lshl_add_u64 v[158:159], v[132:133], 0, v[156:157]
	global_store_dwordx4 v[158:159], v[152:155], off offset:256
	s_nop 1
	s_cbranch_scc1 .LBB0_1288
	v_mov_b32_e32 v132, v128
	v_mov_b32_e32 v133, v126
	v_mov_b32_e32 v134, v129
	v_mov_b32_e32 v135, v126
	v_pk_add_f32 v[136:137], v[132:133], v[134:135]
	v_pk_mul_f32 v[132:133], v[132:133], v[134:135]
	v_mul_f32_e32 v135, v124, v124
	v_mov_b32_e32 v137, v133
	v_pk_add_f32 v[132:133], v[126:127], v[126:127] op_sel:[1,0]
	v_pk_mul_f32 v[126:127], v[126:127], v[126:127]
	v_mov_b32_e32 v134, v124
	v_mov_b32_e32 v133, v127
	v_pk_add_f32 v[126:127], v[132:133], v[136:137]
	v_mul_f32_e32 v132, v128, v128
	v_pk_fma_f32 v[128:129], v[128:129], v[128:129], v[132:133] op_sel_hi:[1,1,0]
	v_mul_f32_e32 v133, v123, v123
	v_mov_b32_e32 v128, v65
	v_pk_add_f32 v[126:127], v[126:127], v[128:129]
	v_mul_f32_e32 v129, v122, v122
	v_mul_f32_e32 v137, v125, v125
	v_mov_b32_e32 v128, v122
	v_mov_b32_e32 v132, v123
	v_mov_b32_e32 v136, v125
	v_pk_add_f32 v[122:123], v[128:129], v[132:133]
	v_pk_add_f32 v[124:125], v[134:135], v[136:137]
	v_mul_f32_e32 v129, v120, v120
	v_pk_add_f32 v[122:123], v[122:123], v[124:125]
	v_mul_f32_e32 v125, v118, v118
	v_pk_add_f32 v[122:123], v[126:127], v[122:123]
	v_mul_f32_e32 v127, v119, v119
	v_mul_f32_e32 v133, v121, v121
	v_mov_b32_e32 v124, v118
	v_mov_b32_e32 v126, v119
	v_mov_b32_e32 v128, v120
	v_mov_b32_e32 v132, v121
	v_pk_add_f32 v[118:119], v[124:125], v[126:127]
	v_pk_add_f32 v[120:121], v[128:129], v[132:133]
	v_cmp_lt_i32_e32 vcc, v206, v204
	v_pk_add_f32 v[118:119], v[118:119], v[120:121]
	v_mul_f32_e32 v121, v114, v114
	v_cndmask_b32_e32 v120, v203, v206, vcc
	v_pk_add_f32 v[118:119], v[122:123], v[118:119]
	v_mul_f32_e32 v123, v115, v115
	v_mul_f32_e32 v125, v116, v116
	v_mul_f32_e32 v127, v117, v117
	v_lshlrev_b32_e32 v128, 2, v120
	v_mov_b32_e32 v120, v114
	v_mov_b32_e32 v122, v115
	v_mov_b32_e32 v124, v116
	v_mov_b32_e32 v126, v117
	v_pk_add_f32 v[114:115], v[120:121], v[122:123]
	v_pk_add_f32 v[116:117], v[124:125], v[126:127]
	v_cmp_lt_i32_e32 vcc, v205, v204
	v_pk_add_f32 v[114:115], v[114:115], v[116:117]
	s_nop 0
	v_pk_add_f32 v[114:115], v[118:119], v[114:115]
	ds_bpermute_b32 v116, v128, v114
	ds_bpermute_b32 v117, v128, v115
	v_cndmask_b32_e32 v118, v203, v205, vcc
	v_lshlrev_b32_e32 v118, 2, v118
	s_waitcnt lgkmcnt(0)
	v_pk_add_f32 v[114:115], v[114:115], v[116:117]
	ds_bpermute_b32 v116, v118, v114
	ds_bpermute_b32 v117, v118, v115
	s_and_saveexec_b64 s[2:3], s[6:7]
	s_cbranch_execz .LBB0_1287
	v_readlane_b32 s4, v249, 5
	v_lshlrev_b64 v[118:119], 7, v[130:131]
	v_readlane_b32 s5, v249, 6
	s_waitcnt lgkmcnt(0)
	v_pk_add_f32 v[114:115], v[114:115], v[116:117]
	v_lshl_add_u64 v[118:119], s[4:5], 0, v[118:119]
	v_lshl_add_u64 v[118:119], s[94:95], 3, v[118:119]
	global_store_dwordx2 v[118:119], v[114:115], off

; __device__ __forceinline__ unsigned cvt_pk_bf16(float lo, float hi) { unsigned r; asm volatile("v_cvt_pk_bf16_f32 %0, %1, %2" : "=v"(r) : "v"(lo), "v"(hi)); return r; }
; __device__ __forceinline__ f32x4 gelu4(const f32x4 x) {
;     const f32x4 t = x * x, a = x * (t * -0.10294324f + -2.3022082f);
;     f32x4 e; e[0] = __builtin_amdgcn_exp2f(a[0]); e[1] = __builtin_amdgcn_exp2f(a[1]); e[2] = __builtin_amdgcn_exp2f(a[2]); e[3] = __builtin_amdgcn_exp2f(a[3]);
;     const f32x4 d = e + 1.0f;
;     f32x4 r; r[0] = __builtin_amdgcn_rcpf(d[0]); r[1] = __builtin_amdgcn_rcpf(d[1]); r[2] = __builtin_amdgcn_rcpf(d[2]); r[3] = __builtin_amdgcn_rcpf(d[3]);
;     return x * r;
; }
;     __device__ __forceinline__ void operator()(const f32x4 (&acc)[2][2][4][2], const Unit& u, int wr, int wc, int fr, int fq) const {
;     ...
;             for (int m = 0; m < 4; ++m) {
;                 const int row = row0 + ai * HALF + m * 16; bf16_t* rowp = proj + (size_t)row * INW + col0; float s = 0.f, q = 0.f;
; #pragma unroll
;                 for (int bj = 0; bj < 2; ++bj)
; #pragma unroll
;                     for (int n = 0; n < 2; ++n) { f32x4 v = acc[ai][bj][m][n];
;                         if (act) v = gelu4(v);
;                         s += (v[0] + v[1]) + (v[2] + v[3]); q += (v[0] * v[0] + v[1] * v[1]) + (v[2] * v[2] + v[3] * v[3]);
;                         u32x2 pk; pk.x = cvt_pk_bf16(v[0], v[1]); pk.y = cvt_pk_bf16(v[2], v[3]); *(u32x2*)(rowp + bj * HALF + n * 16) = pk; }
;                 if (st) { s += __shfl_xor(s, 16); s += __shfl_xor(s, 32); q += __shfl_xor(q, 16); q += __shfl_xor(q, 32);
;                     if (fq == 0) { float* sp = stats + ((size_t)row * 16 + (u.pn - 6) * 4 + wc) * 2; sp[0] = s; sp[1] = q; } }
.LBB0_1290:
	v_or_b32_e32 v114, 16, v130
	v_ashrrev_i32_e32 v115, 31, v114
	s_waitcnt lgkmcnt(0)
	v_lshlrev_b64 v[116:117], 13, v[114:115]
	v_lshl_add_u64 v[116:117], s[80:81], 0, v[116:117]
	v_lshl_add_u64 v[116:117], v[116:117], 0, v[64:65]
	s_and_b64 vcc, exec, s[0:1]
	v_cvt_pk_bf16_f32 v152, v110, v111
	v_cvt_pk_bf16_f32 v153, v112, v113
	s_cbranch_vccnz .LBB0_1292
	s_mov_b32 s2, 0xc0135761
	v_pk_mul_f32 v[118:119], v[108:109], v[108:109]
	v_pk_mul_f32 v[120:121], v[106:107], v[106:107]
	v_mov_b64_e32 v[122:123], s[2:3]
	s_mov_b32 s2, 0xbdd2d3e8
	v_pk_fma_f32 v[118:119], v[118:119], s[2:3], v[122:123] op_sel_hi:[1,0,0]
	v_pk_fma_f32 v[120:121], v[120:121], s[2:3], v[122:123] op_sel_hi:[1,0,0]
	v_pk_mul_f32 v[118:119], v[108:109], v[118:119]
	v_pk_mul_f32 v[120:121], v[106:107], v[120:121]
	v_exp_f32_e32 v118, v118
	v_exp_f32_e32 v120, v120
	v_exp_f32_e32 v119, v119
	v_exp_f32_e32 v121, v121
	v_pk_add_f32 v[118:119], v[118:119], 1.0 op_sel_hi:[1,0]
	v_pk_add_f32 v[120:121], v[120:121], 1.0 op_sel_hi:[1,0]
	v_rcp_f32_e32 v118, v118
	v_rcp_f32_e32 v120, v120
	v_rcp_f32_e32 v119, v119
	v_rcp_f32_e32 v121, v121
	v_pk_mul_f32 v[108:109], v[108:109], v[118:119]
	v_pk_mul_f32 v[106:107], v[106:107], v[120:121]
.LBB0_1292:
	s_and_b64 vcc, exec, s[0:1]
	v_cvt_pk_bf16_f32 v154, v106, v107
	v_cvt_pk_bf16_f32 v155, v108, v109
	s_nop 1
	v_permlane16_swap_b32_e32 v152, v154
	v_permlane16_swap_b32_e32 v153, v155
	v_lshl_add_u64 v[158:159], v[116:117], 0, v[156:157]
	global_store_dwordx4 v[158:159], v[152:155], off
	s_nop 1
	s_cbranch_vccnz .LBB0_1294
	s_mov_b32 s2, 0xc0135761
	v_pk_mul_f32 v[118:119], v[104:105], v[104:105]
	v_pk_mul_f32 v[120:121], v[102:103], v[102:103]
	v_mov_b64_e32 v[122:123], s[2:3]
	s_mov_b32 s2, 0xbdd2d3e8
	v_pk_fma_f32 v[118:119], v[118:119], s[2:3], v[122:123] op_sel_hi:[1,0,0]
	v_pk_fma_f32 v[120:121], v[120:121], s[2:3], v[122:123] op_sel_hi:[1,0,0]
	v_pk_mul_f32 v[118:119], v[104:105], v[118:119]
	v_pk_mul_f32 v[120:121], v[102:103], v[120:121]
	v_exp_f32_e32 v118, v118
	v_exp_f32_e32 v120, v120
	v_exp_f32_e32 v119, v119
	v_exp_f32_e32 v121, v121
	v_pk_add_f32 v[118:119], v[118:119], 1.0 op_sel_hi:[1,0]
	v_pk_add_f32 v[120:121], v[120:121], 1.0 op_sel_hi:[1,0]
	v_rcp_f32_e32 v118, v118
	v_rcp_f32_e32 v120, v120
	v_rcp_f32_e32 v119, v119
	v_rcp_f32_e32 v121, v121
	v_pk_mul_f32 v[104:105], v[104:105], v[118:119]
	v_pk_mul_f32 v[102:103], v[102:103], v[120:121]
.LBB0_1294:
	s_and_b64 vcc, exec, s[0:1]
	v_cvt_pk_bf16_f32 v152, v102, v103
	v_cvt_pk_bf16_f32 v153, v104, v105
	s_cbranch_vccnz .LBB0_1296
	s_mov_b32 s2, 0xc0135761
	v_pk_mul_f32 v[118:119], v[100:101], v[100:101]
	v_pk_mul_f32 v[120:121], v[98:99], v[98:99]
	v_mov_b64_e32 v[122:123], s[2:3]
	s_mov_b32 s2, 0xbdd2d3e8
	v_pk_fma_f32 v[118:119], v[118:119], s[2:3], v[122:123] op_sel_hi:[1,0,0]
	v_pk_fma_f32 v[120:121], v[120:121], s[2:3], v[122:123] op_sel_hi:[1,0,0]
	v_pk_mul_f32 v[118:119], v[100:101], v[118:119]
	v_pk_mul_f32 v[120:121], v[98:99], v[120:121]
	v_exp_f32_e32 v118, v118
	v_exp_f32_e32 v120, v120
	v_exp_f32_e32 v119, v119
	v_exp_f32_e32 v121, v121
	v_pk_add_f32 v[118:119], v[118:119], 1.0 op_sel_hi:[1,0]
	v_pk_add_f32 v[120:121], v[120:121], 1.0 op_sel_hi:[1,0]
	v_rcp_f32_e32 v118, v118
	v_rcp_f32_e32 v120, v120
	v_rcp_f32_e32 v119, v119
	v_rcp_f32_e32 v121, v121
	v_pk_mul_f32 v[100:101], v[100:101], v[118:119]
	v_pk_mul_f32 v[98:99], v[98:99], v[120:121]
.LBB0_1296:
	s_nop 0
	v_cvt_pk_bf16_f32 v154, v98, v99
	v_cvt_pk_bf16_f32 v155, v100, v101
	s_nop 1
	v_permlane16_swap_b32_e32 v152, v154
	v_permlane16_swap_b32_e32 v153, v155
	v_lshl_add_u64 v[158:159], v[116:117], 0, v[156:157]
	global_store_dwordx4 v[158:159], v[152:155], off offset:256
	s_nop 1
	v_cndmask_b32_e64 v116, 0, 1, s[8:9]
	v_cmp_ne_u32_e64 s[4:5], 1, v116
	s_andn2_b64 vcc, exec, s[8:9]
	s_cbranch_vccnz .LBB0_1300
	v_mov_b32_e32 v116, v112
	v_mov_b32_e32 v117, v110
	v_mov_b32_e32 v118, v113
	v_mov_b32_e32 v119, v110
	v_pk_add_f32 v[120:121], v[116:117], v[118:119]
	v_pk_mul_f32 v[116:117], v[116:117], v[118:119]
	v_mul_f32_e32 v119, v108, v108
	v_mov_b32_e32 v121, v117
	v_pk_add_f32 v[116:117], v[110:111], v[110:111] op_sel:[1,0]
	v_pk_mul_f32 v[110:111], v[110:111], v[110:111]
	v_mov_b32_e32 v118, v108
	v_mov_b32_e32 v117, v111
	v_pk_add_f32 v[110:111], v[116:117], v[120:121]
	v_mul_f32_e32 v116, v112, v112
	v_pk_fma_f32 v[112:113], v[112:113], v[112:113], v[116:117] op_sel_hi:[1,1,0]
	v_mul_f32_e32 v117, v107, v107
	v_mov_b32_e32 v112, v65
	v_pk_add_f32 v[110:111], v[110:111], v[112:113]
	v_mul_f32_e32 v113, v106, v106
	v_mul_f32_e32 v121, v109, v109
	v_mov_b32_e32 v112, v106
	v_mov_b32_e32 v116, v107
	v_mov_b32_e32 v120, v109
	v_pk_add_f32 v[106:107], v[112:113], v[116:117]
	v_pk_add_f32 v[108:109], v[118:119], v[120:121]
	v_mul_f32_e32 v113, v104, v104
	v_pk_add_f32 v[106:107], v[106:107], v[108:109]
	v_mul_f32_e32 v109, v102, v102
	v_pk_add_f32 v[106:107], v[110:111], v[106:107]
	v_mul_f32_e32 v111, v103, v103
	v_mul_f32_e32 v117, v105, v105
	v_mov_b32_e32 v108, v102
	v_mov_b32_e32 v110, v103
	v_mov_b32_e32 v112, v104
	v_mov_b32_e32 v116, v105
	v_pk_add_f32 v[102:103], v[108:109], v[110:111]
	v_pk_add_f32 v[104:105], v[112:113], v[116:117]
	v_cmp_lt_i32_e32 vcc, v206, v204
	v_pk_add_f32 v[102:103], v[102:103], v[104:105]
	v_mul_f32_e32 v105, v98, v98
	v_cndmask_b32_e32 v104, v203, v206, vcc
	v_pk_add_f32 v[102:103], v[106:107], v[102:103]
	v_mul_f32_e32 v107, v99, v99
	v_mul_f32_e32 v109, v100, v100
	v_mul_f32_e32 v111, v101, v101
	v_lshlrev_b32_e32 v112, 2, v104
	v_mov_b32_e32 v104, v98
	v_mov_b32_e32 v106, v99
	v_mov_b32_e32 v108, v100
	v_mov_b32_e32 v110, v101
	v_pk_add_f32 v[98:99], v[104:105], v[106:107]
	v_pk_add_f32 v[100:101], v[108:109], v[110:111]
	v_cmp_lt_i32_e32 vcc, v205, v204
	v_pk_add_f32 v[98:99], v[98:99], v[100:101]
	s_nop 0
	v_pk_add_f32 v[98:99], v[102:103], v[98:99]
	ds_bpermute_b32 v100, v112, v98
	ds_bpermute_b32 v101, v112, v99
	v_cndmask_b32_e32 v102, v203, v205, vcc
	v_lshlrev_b32_e32 v102, 2, v102
	s_waitcnt lgkmcnt(0)
	v_pk_add_f32 v[98:99], v[98:99], v[100:101]
	ds_bpermute_b32 v100, v102, v98
	ds_bpermute_b32 v101, v102, v99
	s_and_saveexec_b64 s[2:3], s[6:7]
	s_cbranch_execz .LBB0_1299
	v_readlane_b32 s8, v249, 5
	v_lshlrev_b64 v[102:103], 7, v[114:115]
	v_readlane_b32 s9, v249, 6
	s_waitcnt lgkmcnt(0)
	v_pk_add_f32 v[98:99], v[98:99], v[100:101]
	v_lshl_add_u64 v[102:103], s[8:9], 0, v[102:103]
	v_lshl_add_u64 v[102:103], s[94:95], 3, v[102:103]
	global_store_dwordx2 v[102:103], v[98:99], off

; __device__ __forceinline__ unsigned cvt_pk_bf16(float lo, float hi) { unsigned r; asm volatile("v_cvt_pk_bf16_f32 %0, %1, %2" : "=v"(r) : "v"(lo), "v"(hi)); return r; }
; __device__ __forceinline__ f32x4 gelu4(const f32x4 x) {
;     const f32x4 t = x * x, a = x * (t * -0.10294324f + -2.3022082f);
;     f32x4 e; e[0] = __builtin_amdgcn_exp2f(a[0]); e[1] = __builtin_amdgcn_exp2f(a[1]); e[2] = __builtin_amdgcn_exp2f(a[2]); e[3] = __builtin_amdgcn_exp2f(a[3]);
;     const f32x4 d = e + 1.0f;
;     f32x4 r; r[0] = __builtin_amdgcn_rcpf(d[0]); r[1] = __builtin_amdgcn_rcpf(d[1]); r[2] = __builtin_amdgcn_rcpf(d[2]); r[3] = __builtin_amdgcn_rcpf(d[3]);
;     return x * r;
; }
;     __device__ __forceinline__ void operator()(const f32x4 (&acc)[2][2][4][2], const Unit& u, int wr, int wc, int fr, int fq) const {
;     ...
;             for (int m = 0; m < 4; ++m) {
;                 const int row = row0 + ai * HALF + m * 16; bf16_t* rowp = proj + (size_t)row * INW + col0; float s = 0.f, q = 0.f;
; #pragma unroll
;                 for (int bj = 0; bj < 2; ++bj)
; #pragma unroll
;                     for (int n = 0; n < 2; ++n) { f32x4 v = acc[ai][bj][m][n];
;                         if (act) v = gelu4(v);
;                         s += (v[0] + v[1]) + (v[2] + v[3]); q += (v[0] * v[0] + v[1] * v[1]) + (v[2] * v[2] + v[3] * v[3]);
;                         u32x2 pk; pk.x = cvt_pk_bf16(v[0], v[1]); pk.y = cvt_pk_bf16(v[2], v[3]); *(u32x2*)(rowp + bj * HALF + n * 16) = pk; }
;                 if (st) { s += __shfl_xor(s, 16); s += __shfl_xor(s, 32); q += __shfl_xor(q, 16); q += __shfl_xor(q, 32);
;                     if (fq == 0) { float* sp = stats + ((size_t)row * 16 + (u.pn - 6) * 4 + wc) * 2; sp[0] = s; sp[1] = q; } }
.LBB0_1302:
	v_or_b32_e32 v98, 32, v130
	v_ashrrev_i32_e32 v99, 31, v98
	s_waitcnt lgkmcnt(0)
	v_lshlrev_b64 v[100:101], 13, v[98:99]
	v_lshl_add_u64 v[100:101], s[80:81], 0, v[100:101]
	v_lshl_add_u64 v[100:101], v[100:101], 0, v[64:65]
	s_and_b64 vcc, exec, s[0:1]
	v_cvt_pk_bf16_f32 v152, v94, v95
	v_cvt_pk_bf16_f32 v153, v96, v97
	s_cbranch_vccnz .LBB0_1304
	s_mov_b32 s2, 0xc0135761
	v_pk_mul_f32 v[102:103], v[92:93], v[92:93]
	v_pk_mul_f32 v[104:105], v[90:91], v[90:91]
	v_mov_b64_e32 v[106:107], s[2:3]
	s_mov_b32 s2, 0xbdd2d3e8
	v_pk_fma_f32 v[102:103], v[102:103], s[2:3], v[106:107] op_sel_hi:[1,0,0]
	v_pk_fma_f32 v[104:105], v[104:105], s[2:3], v[106:107] op_sel_hi:[1,0,0]
	v_pk_mul_f32 v[102:103], v[92:93], v[102:103]
	v_pk_mul_f32 v[104:105], v[90:91], v[104:105]
	v_exp_f32_e32 v102, v102
	v_exp_f32_e32 v104, v104
	v_exp_f32_e32 v103, v103
	v_exp_f32_e32 v105, v105
	v_pk_add_f32 v[102:103], v[102:103], 1.0 op_sel_hi:[1,0]
	v_pk_add_f32 v[104:105], v[104:105], 1.0 op_sel_hi:[1,0]
	v_rcp_f32_e32 v102, v102
	v_rcp_f32_e32 v104, v104
	v_rcp_f32_e32 v103, v103
	v_rcp_f32_e32 v105, v105
	v_pk_mul_f32 v[92:93], v[92:93], v[102:103]
	v_pk_mul_f32 v[90:91], v[90:91], v[104:105]
.LBB0_1304:
	s_and_b64 vcc, exec, s[0:1]
	v_cvt_pk_bf16_f32 v154, v90, v91
	v_cvt_pk_bf16_f32 v155, v92, v93
	s_nop 1
	v_permlane16_swap_b32_e32 v152, v154
	v_permlane16_swap_b32_e32 v153, v155
	v_lshl_add_u64 v[158:159], v[100:101], 0, v[156:157]
	global_store_dwordx4 v[158:159], v[152:155], off
	s_nop 1
	s_cbranch_vccnz .LBB0_1306
	s_mov_b32 s2, 0xc0135761
	v_pk_mul_f32 v[102:103], v[88:89], v[88:89]
	v_pk_mul_f32 v[104:105], v[86:87], v[86:87]
	v_mov_b64_e32 v[106:107], s[2:3]
	s_mov_b32 s2, 0xbdd2d3e8
	v_pk_fma_f32 v[102:103], v[102:103], s[2:3], v[106:107] op_sel_hi:[1,0,0]
	v_pk_fma_f32 v[104:105], v[104:105], s[2:3], v[106:107] op_sel_hi:[1,0,0]
	v_pk_mul_f32 v[102:103], v[88:89], v[102:103]
	v_pk_mul_f32 v[104:105], v[86:87], v[104:105]
	v_exp_f32_e32 v102, v102
	v_exp_f32_e32 v104, v104
	v_exp_f32_e32 v103, v103
	v_exp_f32_e32 v105, v105
	v_pk_add_f32 v[102:103], v[102:103], 1.0 op_sel_hi:[1,0]
	v_pk_add_f32 v[104:105], v[104:105], 1.0 op_sel_hi:[1,0]
	v_rcp_f32_e32 v102, v102
	v_rcp_f32_e32 v104, v104
	v_rcp_f32_e32 v103, v103
	v_rcp_f32_e32 v105, v105
	v_pk_mul_f32 v[88:89], v[88:89], v[102:103]
	v_pk_mul_f32 v[86:87], v[86:87], v[104:105]
.LBB0_1306:
	s_and_b64 vcc, exec, s[0:1]
	v_cvt_pk_bf16_f32 v152, v86, v87
	v_cvt_pk_bf16_f32 v153, v88, v89
	s_cbranch_vccnz .LBB0_1308
	s_mov_b32 s2, 0xc0135761
	v_pk_mul_f32 v[102:103], v[84:85], v[84:85]
	v_pk_mul_f32 v[104:105], v[82:83], v[82:83]
	v_mov_b64_e32 v[106:107], s[2:3]
	s_mov_b32 s2, 0xbdd2d3e8
	v_pk_fma_f32 v[102:103], v[102:103], s[2:3], v[106:107] op_sel_hi:[1,0,0]
	v_pk_fma_f32 v[104:105], v[104:105], s[2:3], v[106:107] op_sel_hi:[1,0,0]
	v_pk_mul_f32 v[102:103], v[84:85], v[102:103]
	v_pk_mul_f32 v[104:105], v[82:83], v[104:105]
	v_exp_f32_e32 v102, v102
	v_exp_f32_e32 v104, v104
	v_exp_f32_e32 v103, v103
	v_exp_f32_e32 v105, v105
	v_pk_add_f32 v[102:103], v[102:103], 1.0 op_sel_hi:[1,0]
	v_pk_add_f32 v[104:105], v[104:105], 1.0 op_sel_hi:[1,0]
	v_rcp_f32_e32 v102, v102
	v_rcp_f32_e32 v104, v104
	v_rcp_f32_e32 v103, v103
	v_rcp_f32_e32 v105, v105
	v_pk_mul_f32 v[84:85], v[84:85], v[102:103]
	v_pk_mul_f32 v[82:83], v[82:83], v[104:105]
.LBB0_1308:
	s_and_b64 vcc, exec, s[4:5]
	v_cvt_pk_bf16_f32 v154, v82, v83
	v_cvt_pk_bf16_f32 v155, v84, v85
	s_nop 1
	v_permlane16_swap_b32_e32 v152, v154
	v_permlane16_swap_b32_e32 v153, v155
	v_lshl_add_u64 v[158:159], v[100:101], 0, v[156:157]
	global_store_dwordx4 v[158:159], v[152:155], off offset:256
	s_nop 1
	s_cbranch_vccnz .LBB0_1312
	v_mov_b32_e32 v100, v96
	v_mov_b32_e32 v101, v94
	v_mov_b32_e32 v102, v97
	v_mov_b32_e32 v103, v94
	v_pk_add_f32 v[104:105], v[100:101], v[102:103]
	v_pk_mul_f32 v[100:101], v[100:101], v[102:103]
	v_mul_f32_e32 v103, v92, v92
	v_mov_b32_e32 v105, v101
	v_pk_add_f32 v[100:101], v[94:95], v[94:95] op_sel:[1,0]
	v_pk_mul_f32 v[94:95], v[94:95], v[94:95]
	v_mov_b32_e32 v102, v92
	v_mov_b32_e32 v101, v95
	v_pk_add_f32 v[94:95], v[100:101], v[104:105]
	v_mul_f32_e32 v100, v96, v96
	v_pk_fma_f32 v[96:97], v[96:97], v[96:97], v[100:101] op_sel_hi:[1,1,0]
	v_mul_f32_e32 v101, v91, v91
	v_mov_b32_e32 v96, v65
	v_pk_add_f32 v[94:95], v[94:95], v[96:97]
	v_mul_f32_e32 v97, v90, v90
	v_mul_f32_e32 v105, v93, v93
	v_mov_b32_e32 v96, v90
	v_mov_b32_e32 v100, v91
	v_mov_b32_e32 v104, v93
	v_pk_add_f32 v[90:91], v[96:97], v[100:101]
	v_pk_add_f32 v[92:93], v[102:103], v[104:105]
	v_mul_f32_e32 v97, v88, v88
	v_pk_add_f32 v[90:91], v[90:91], v[92:93]
	v_mul_f32_e32 v93, v86, v86
	v_pk_add_f32 v[90:91], v[94:95], v[90:91]
	v_mul_f32_e32 v95, v87, v87
	v_mul_f32_e32 v101, v89, v89
	v_mov_b32_e32 v92, v86
	v_mov_b32_e32 v94, v87
	v_mov_b32_e32 v96, v88
	v_mov_b32_e32 v100, v89
	v_pk_add_f32 v[86:87], v[92:93], v[94:95]
	v_pk_add_f32 v[88:89], v[96:97], v[100:101]
	v_cmp_lt_i32_e32 vcc, v206, v204
	v_pk_add_f32 v[86:87], v[86:87], v[88:89]
	v_mul_f32_e32 v89, v82, v82
	v_cndmask_b32_e32 v88, v203, v206, vcc
	v_pk_add_f32 v[86:87], v[90:91], v[86:87]
	v_mul_f32_e32 v91, v83, v83
	v_mul_f32_e32 v93, v84, v84
	v_mul_f32_e32 v95, v85, v85
	v_lshlrev_b32_e32 v96, 2, v88
	v_mov_b32_e32 v88, v82
	v_mov_b32_e32 v90, v83
	v_mov_b32_e32 v92, v84
	v_mov_b32_e32 v94, v85
	v_pk_add_f32 v[82:83], v[88:89], v[90:91]
	v_pk_add_f32 v[84:85], v[92:93], v[94:95]
	v_cmp_lt_i32_e32 vcc, v205, v204
	v_pk_add_f32 v[82:83], v[82:83], v[84:85]
	s_nop 0
	v_pk_add_f32 v[82:83], v[86:87], v[82:83]
	ds_bpermute_b32 v84, v96, v82
	ds_bpermute_b32 v85, v96, v83
	v_cndmask_b32_e32 v86, v203, v205, vcc
	v_lshlrev_b32_e32 v86, 2, v86
	s_waitcnt lgkmcnt(0)
	v_pk_add_f32 v[82:83], v[82:83], v[84:85]
	ds_bpermute_b32 v84, v86, v82
	ds_bpermute_b32 v85, v86, v83
	s_and_saveexec_b64 s[2:3], s[6:7]
	s_cbranch_execz .LBB0_1311
	v_readlane_b32 s8, v249, 5
	v_lshlrev_b64 v[86:87], 7, v[98:99]
	v_readlane_b32 s9, v249, 6
	s_waitcnt lgkmcnt(0)
	v_pk_add_f32 v[82:83], v[82:83], v[84:85]
	v_lshl_add_u64 v[86:87], s[8:9], 0, v[86:87]
	v_lshl_add_u64 v[86:87], s[94:95], 3, v[86:87]
	global_store_dwordx2 v[86:87], v[82:83], off

; __device__ __forceinline__ unsigned cvt_pk_bf16(float lo, float hi) { unsigned r; asm volatile("v_cvt_pk_bf16_f32 %0, %1, %2" : "=v"(r) : "v"(lo), "v"(hi)); return r; }
; __device__ __forceinline__ f32x4 gelu4(const f32x4 x) {
;     const f32x4 t = x * x, a = x * (t * -0.10294324f + -2.3022082f);
;     f32x4 e; e[0] = __builtin_amdgcn_exp2f(a[0]); e[1] = __builtin_amdgcn_exp2f(a[1]); e[2] = __builtin_amdgcn_exp2f(a[2]); e[3] = __builtin_amdgcn_exp2f(a[3]);
;     const f32x4 d = e + 1.0f;
;     f32x4 r; r[0] = __builtin_amdgcn_rcpf(d[0]); r[1] = __builtin_amdgcn_rcpf(d[1]); r[2] = __builtin_amdgcn_rcpf(d[2]); r[3] = __builtin_amdgcn_rcpf(d[3]);
;     return x * r;
; }
;     __device__ __forceinline__ void operator()(const f32x4 (&acc)[2][2][4][2], const Unit& u, int wr, int wc, int fr, int fq) const {
;     ...
;             for (int m = 0; m < 4; ++m) {
;                 const int row = row0 + ai * HALF + m * 16; bf16_t* rowp = proj + (size_t)row * INW + col0; float s = 0.f, q = 0.f;
; #pragma unroll
;                 for (int bj = 0; bj < 2; ++bj)
; #pragma unroll
;                     for (int n = 0; n < 2; ++n) { f32x4 v = acc[ai][bj][m][n];
;                         if (act) v = gelu4(v);
;                         s += (v[0] + v[1]) + (v[2] + v[3]); q += (v[0] * v[0] + v[1] * v[1]) + (v[2] * v[2] + v[3] * v[3]);
;                         u32x2 pk; pk.x = cvt_pk_bf16(v[0], v[1]); pk.y = cvt_pk_bf16(v[2], v[3]); *(u32x2*)(rowp + bj * HALF + n * 16) = pk; }
;                 if (st) { s += __shfl_xor(s, 16); s += __shfl_xor(s, 32); q += __shfl_xor(q, 16); q += __shfl_xor(q, 32);
;                     if (fq == 0) { float* sp = stats + ((size_t)row * 16 + (u.pn - 6) * 4 + wc) * 2; sp[0] = s; sp[1] = q; } }
.LBB0_1314:
	v_or_b32_e32 v82, 48, v130
	v_ashrrev_i32_e32 v83, 31, v82
	s_waitcnt lgkmcnt(0)
	v_lshlrev_b64 v[84:85], 13, v[82:83]
	v_lshl_add_u64 v[84:85], s[80:81], 0, v[84:85]
	v_lshl_add_u64 v[84:85], v[84:85], 0, v[64:65]
	s_and_b64 vcc, exec, s[0:1]
	v_cvt_pk_bf16_f32 v152, v78, v79
	v_cvt_pk_bf16_f32 v153, v80, v81
	s_cbranch_vccnz .LBB0_1316
	s_mov_b32 s2, 0xc0135761
	v_pk_mul_f32 v[86:87], v[76:77], v[76:77]
	v_pk_mul_f32 v[88:89], v[74:75], v[74:75]
	v_mov_b64_e32 v[90:91], s[2:3]
	s_mov_b32 s2, 0xbdd2d3e8
	v_pk_fma_f32 v[86:87], v[86:87], s[2:3], v[90:91] op_sel_hi:[1,0,0]
	v_pk_fma_f32 v[88:89], v[88:89], s[2:3], v[90:91] op_sel_hi:[1,0,0]
	v_pk_mul_f32 v[86:87], v[76:77], v[86:87]
	v_pk_mul_f32 v[88:89], v[74:75], v[88:89]
	v_exp_f32_e32 v86, v86
	v_exp_f32_e32 v88, v88
	v_exp_f32_e32 v87, v87
	v_exp_f32_e32 v89, v89
	v_pk_add_f32 v[86:87], v[86:87], 1.0 op_sel_hi:[1,0]
	v_pk_add_f32 v[88:89], v[88:89], 1.0 op_sel_hi:[1,0]
	v_rcp_f32_e32 v86, v86
	v_rcp_f32_e32 v88, v88
	v_rcp_f32_e32 v87, v87
	v_rcp_f32_e32 v89, v89
	v_pk_mul_f32 v[76:77], v[76:77], v[86:87]
	v_pk_mul_f32 v[74:75], v[74:75], v[88:89]
.LBB0_1316:
	s_and_b64 vcc, exec, s[0:1]
	v_cvt_pk_bf16_f32 v154, v74, v75
	v_cvt_pk_bf16_f32 v155, v76, v77
	s_nop 1
	v_permlane16_swap_b32_e32 v152, v154
	v_permlane16_swap_b32_e32 v153, v155
	v_lshl_add_u64 v[158:159], v[84:85], 0, v[156:157]
	global_store_dwordx4 v[158:159], v[152:155], off
	s_nop 1
	s_cbranch_vccnz .LBB0_1318
	s_mov_b32 s2, 0xc0135761
	v_pk_mul_f32 v[86:87], v[72:73], v[72:73]
	v_pk_mul_f32 v[88:89], v[70:71], v[70:71]
	v_mov_b64_e32 v[90:91], s[2:3]
	s_mov_b32 s2, 0xbdd2d3e8
	v_pk_fma_f32 v[86:87], v[86:87], s[2:3], v[90:91] op_sel_hi:[1,0,0]
	v_pk_fma_f32 v[88:89], v[88:89], s[2:3], v[90:91] op_sel_hi:[1,0,0]
	v_pk_mul_f32 v[86:87], v[72:73], v[86:87]
	v_pk_mul_f32 v[88:89], v[70:71], v[88:89]
	v_exp_f32_e32 v86, v86
	v_exp_f32_e32 v88, v88
	v_exp_f32_e32 v87, v87
	v_exp_f32_e32 v89, v89
	v_pk_add_f32 v[86:87], v[86:87], 1.0 op_sel_hi:[1,0]
	v_pk_add_f32 v[88:89], v[88:89], 1.0 op_sel_hi:[1,0]
	v_rcp_f32_e32 v86, v86
	v_rcp_f32_e32 v88, v88
	v_rcp_f32_e32 v87, v87
	v_rcp_f32_e32 v89, v89
	v_pk_mul_f32 v[72:73], v[72:73], v[86:87]
	v_pk_mul_f32 v[70:71], v[70:71], v[88:89]
.LBB0_1318:
	s_and_b64 vcc, exec, s[0:1]
	v_cvt_pk_bf16_f32 v152, v70, v71
	v_cvt_pk_bf16_f32 v153, v72, v73
	s_cbranch_vccnz .LBB0_1320
	s_mov_b32 s2, 0xc0135761
	v_pk_mul_f32 v[86:87], v[68:69], v[68:69]
	v_pk_mul_f32 v[88:89], v[66:67], v[66:67]
	v_mov_b64_e32 v[90:91], s[2:3]
	s_mov_b32 s2, 0xbdd2d3e8
	v_pk_fma_f32 v[86:87], v[86:87], s[2:3], v[90:91] op_sel_hi:[1,0,0]
	v_pk_fma_f32 v[88:89], v[88:89], s[2:3], v[90:91] op_sel_hi:[1,0,0]
	v_pk_mul_f32 v[86:87], v[68:69], v[86:87]
	v_pk_mul_f32 v[88:89], v[66:67], v[88:89]
	v_exp_f32_e32 v86, v86
	v_exp_f32_e32 v88, v88
	v_exp_f32_e32 v87, v87
	v_exp_f32_e32 v89, v89
	v_pk_add_f32 v[86:87], v[86:87], 1.0 op_sel_hi:[1,0]
	v_pk_add_f32 v[88:89], v[88:89], 1.0 op_sel_hi:[1,0]
	v_rcp_f32_e32 v86, v86
	v_rcp_f32_e32 v88, v88
	v_rcp_f32_e32 v87, v87
	v_rcp_f32_e32 v89, v89
	v_pk_mul_f32 v[68:69], v[68:69], v[86:87]
	v_pk_mul_f32 v[66:67], v[66:67], v[88:89]
.LBB0_1320:
	s_and_b64 vcc, exec, s[4:5]
	v_cvt_pk_bf16_f32 v154, v66, v67
	v_cvt_pk_bf16_f32 v155, v68, v69
	s_nop 1
	v_permlane16_swap_b32_e32 v152, v154
	v_permlane16_swap_b32_e32 v153, v155
	v_lshl_add_u64 v[158:159], v[84:85], 0, v[156:157]
	global_store_dwordx4 v[158:159], v[152:155], off offset:256
	s_nop 1
	s_cbranch_vccnz .LBB0_1324
	v_mov_b32_e32 v84, v80
	v_mov_b32_e32 v85, v78
	v_mov_b32_e32 v86, v81
	v_mov_b32_e32 v87, v78
	v_pk_add_f32 v[88:89], v[84:85], v[86:87]
	v_pk_mul_f32 v[84:85], v[84:85], v[86:87]
	v_mul_f32_e32 v87, v76, v76
	v_mov_b32_e32 v89, v85
	v_pk_add_f32 v[84:85], v[78:79], v[78:79] op_sel:[1,0]
	v_pk_mul_f32 v[78:79], v[78:79], v[78:79]
	v_mov_b32_e32 v86, v76
	v_mov_b32_e32 v85, v79
	v_pk_add_f32 v[78:79], v[84:85], v[88:89]
	v_mul_f32_e32 v84, v80, v80
	v_pk_fma_f32 v[80:81], v[80:81], v[80:81], v[84:85] op_sel_hi:[1,1,0]
	v_mul_f32_e32 v85, v75, v75
	v_mov_b32_e32 v80, v65
	v_pk_add_f32 v[78:79], v[78:79], v[80:81]
	v_mul_f32_e32 v81, v74, v74
	v_mul_f32_e32 v89, v77, v77
	v_mov_b32_e32 v80, v74
	v_mov_b32_e32 v84, v75
	v_mov_b32_e32 v88, v77
	v_pk_add_f32 v[74:75], v[80:81], v[84:85]
	v_pk_add_f32 v[76:77], v[86:87], v[88:89]
	v_mul_f32_e32 v81, v72, v72
	v_pk_add_f32 v[74:75], v[74:75], v[76:77]
	v_mul_f32_e32 v77, v70, v70
	v_pk_add_f32 v[74:75], v[78:79], v[74:75]
	v_mul_f32_e32 v79, v71, v71
	v_mul_f32_e32 v85, v73, v73
	v_mov_b32_e32 v76, v70
	v_mov_b32_e32 v78, v71
	v_mov_b32_e32 v80, v72
	v_mov_b32_e32 v84, v73
	v_pk_add_f32 v[70:71], v[76:77], v[78:79]
	v_pk_add_f32 v[72:73], v[80:81], v[84:85]
	v_cmp_lt_i32_e32 vcc, v206, v204
	v_pk_add_f32 v[70:71], v[70:71], v[72:73]
	v_mul_f32_e32 v73, v66, v66
	v_cndmask_b32_e32 v72, v203, v206, vcc
	v_pk_add_f32 v[70:71], v[74:75], v[70:71]
	v_mul_f32_e32 v75, v67, v67
	v_mul_f32_e32 v77, v68, v68
	v_mul_f32_e32 v79, v69, v69
	v_lshlrev_b32_e32 v80, 2, v72
	v_mov_b32_e32 v72, v66
	v_mov_b32_e32 v74, v67
	v_mov_b32_e32 v76, v68
	v_mov_b32_e32 v78, v69
	v_pk_add_f32 v[66:67], v[72:73], v[74:75]
	v_pk_add_f32 v[68:69], v[76:77], v[78:79]
	v_cmp_lt_i32_e32 vcc, v205, v204
	v_pk_add_f32 v[66:67], v[66:67], v[68:69]
	s_nop 0
	v_pk_add_f32 v[66:67], v[70:71], v[66:67]
	ds_bpermute_b32 v68, v80, v66
	ds_bpermute_b32 v69, v80, v67
	v_cndmask_b32_e32 v70, v203, v205, vcc
	v_lshlrev_b32_e32 v70, 2, v70
	s_waitcnt lgkmcnt(0)
	v_pk_add_f32 v[66:67], v[66:67], v[68:69]
	ds_bpermute_b32 v68, v70, v66
	ds_bpermute_b32 v69, v70, v67
	s_and_saveexec_b64 s[2:3], s[6:7]
	s_cbranch_execz .LBB0_1323
	v_readlane_b32 s8, v249, 5
	v_lshlrev_b64 v[70:71], 7, v[82:83]
	v_readlane_b32 s9, v249, 6
	s_waitcnt lgkmcnt(0)
	v_pk_add_f32 v[66:67], v[66:67], v[68:69]
	v_lshl_add_u64 v[70:71], s[8:9], 0, v[70:71]
	v_lshl_add_u64 v[70:71], s[94:95], 3, v[70:71]
	global_store_dwordx2 v[70:71], v[66:67], off

; __device__ __forceinline__ unsigned cvt_pk_bf16(float lo, float hi) { unsigned r; asm volatile("v_cvt_pk_bf16_f32 %0, %1, %2" : "=v"(r) : "v"(lo), "v"(hi)); return r; }
; __device__ __forceinline__ f32x4 gelu4(const f32x4 x) {
;     const f32x4 t = x * x, a = x * (t * -0.10294324f + -2.3022082f);
;     f32x4 e; e[0] = __builtin_amdgcn_exp2f(a[0]); e[1] = __builtin_amdgcn_exp2f(a[1]); e[2] = __builtin_amdgcn_exp2f(a[2]); e[3] = __builtin_amdgcn_exp2f(a[3]);
;     const f32x4 d = e + 1.0f;
;     f32x4 r; r[0] = __builtin_amdgcn_rcpf(d[0]); r[1] = __builtin_amdgcn_rcpf(d[1]); r[2] = __builtin_amdgcn_rcpf(d[2]); r[3] = __builtin_amdgcn_rcpf(d[3]);
;     return x * r;
; }
;     __device__ __forceinline__ void operator()(const f32x4 (&acc)[2][2][4][2], const Unit& u, int wr, int wc, int fr, int fq) const {
;     ...
;             for (int m = 0; m < 4; ++m) {
;                 const int row = row0 + ai * HALF + m * 16; bf16_t* rowp = proj + (size_t)row * INW + col0; float s = 0.f, q = 0.f;
; #pragma unroll
;                 for (int bj = 0; bj < 2; ++bj)
; #pragma unroll
;                     for (int n = 0; n < 2; ++n) { f32x4 v = acc[ai][bj][m][n];
;                         if (act) v = gelu4(v);
;                         s += (v[0] + v[1]) + (v[2] + v[3]); q += (v[0] * v[0] + v[1] * v[1]) + (v[2] * v[2] + v[3] * v[3]);
;                         u32x2 pk; pk.x = cvt_pk_bf16(v[0], v[1]); pk.y = cvt_pk_bf16(v[2], v[3]); *(u32x2*)(rowp + bj * HALF + n * 16) = pk; }
;                 if (st) { s += __shfl_xor(s, 16); s += __shfl_xor(s, 32); q += __shfl_xor(q, 16); q += __shfl_xor(q, 32);
;                     if (fq == 0) { float* sp = stats + ((size_t)row * 16 + (u.pn - 6) * 4 + wc) * 2; sp[0] = s; sp[1] = q; } }
.LBB0_1326:
	v_add_u32_e32 v66, 0x80, v130
	v_ashrrev_i32_e32 v67, 31, v66
	s_waitcnt lgkmcnt(0)
	v_lshlrev_b64 v[68:69], 13, v[66:67]
	v_lshl_add_u64 v[68:69], s[80:81], 0, v[68:69]
	v_lshl_add_u64 v[68:69], v[68:69], 0, v[64:65]
	s_and_b64 vcc, exec, s[0:1]
	v_cvt_pk_bf16_f32 v152, v60, v61
	v_cvt_pk_bf16_f32 v153, v62, v63
	s_cbranch_vccnz .LBB0_1328
	s_mov_b32 s2, 0xc0135761
	v_pk_mul_f32 v[70:71], v[58:59], v[58:59]
	v_pk_mul_f32 v[72:73], v[56:57], v[56:57]
	v_mov_b64_e32 v[74:75], s[2:3]
	s_mov_b32 s2, 0xbdd2d3e8
	v_pk_fma_f32 v[70:71], v[70:71], s[2:3], v[74:75] op_sel_hi:[1,0,0]
	v_pk_fma_f32 v[72:73], v[72:73], s[2:3], v[74:75] op_sel_hi:[1,0,0]
	v_pk_mul_f32 v[70:71], v[58:59], v[70:71]
	v_pk_mul_f32 v[72:73], v[56:57], v[72:73]
	v_exp_f32_e32 v70, v70
	v_exp_f32_e32 v72, v72
	v_exp_f32_e32 v71, v71
	v_exp_f32_e32 v73, v73
	v_pk_add_f32 v[70:71], v[70:71], 1.0 op_sel_hi:[1,0]
	v_pk_add_f32 v[72:73], v[72:73], 1.0 op_sel_hi:[1,0]
	v_rcp_f32_e32 v70, v70
	v_rcp_f32_e32 v72, v72
	v_rcp_f32_e32 v71, v71
	v_rcp_f32_e32 v73, v73
	v_pk_mul_f32 v[58:59], v[58:59], v[70:71]
	v_pk_mul_f32 v[56:57], v[56:57], v[72:73]
.LBB0_1328:
	s_and_b64 vcc, exec, s[0:1]
	v_cvt_pk_bf16_f32 v154, v56, v57
	v_cvt_pk_bf16_f32 v155, v58, v59
	s_nop 1
	v_permlane16_swap_b32_e32 v152, v154
	v_permlane16_swap_b32_e32 v153, v155
	v_lshl_add_u64 v[158:159], v[68:69], 0, v[156:157]
	global_store_dwordx4 v[158:159], v[152:155], off
	s_nop 1
	s_cbranch_vccnz .LBB0_1330
	s_mov_b32 s2, 0xc0135761
	v_pk_mul_f32 v[70:71], v[54:55], v[54:55]
	v_pk_mul_f32 v[72:73], v[52:53], v[52:53]
	v_mov_b64_e32 v[74:75], s[2:3]
	s_mov_b32 s2, 0xbdd2d3e8
	v_pk_fma_f32 v[70:71], v[70:71], s[2:3], v[74:75] op_sel_hi:[1,0,0]
	v_pk_fma_f32 v[72:73], v[72:73], s[2:3], v[74:75] op_sel_hi:[1,0,0]
	v_pk_mul_f32 v[70:71], v[54:55], v[70:71]
	v_pk_mul_f32 v[72:73], v[52:53], v[72:73]
	v_exp_f32_e32 v70, v70
	v_exp_f32_e32 v72, v72
	v_exp_f32_e32 v71, v71
	v_exp_f32_e32 v73, v73
	v_pk_add_f32 v[70:71], v[70:71], 1.0 op_sel_hi:[1,0]
	v_pk_add_f32 v[72:73], v[72:73], 1.0 op_sel_hi:[1,0]
	v_rcp_f32_e32 v70, v70
	v_rcp_f32_e32 v72, v72
	v_rcp_f32_e32 v71, v71
	v_rcp_f32_e32 v73, v73
	v_pk_mul_f32 v[54:55], v[54:55], v[70:71]
	v_pk_mul_f32 v[52:53], v[52:53], v[72:73]
.LBB0_1330:
	s_and_b64 vcc, exec, s[0:1]
	v_cvt_pk_bf16_f32 v152, v52, v53
	v_cvt_pk_bf16_f32 v153, v54, v55
	s_cbranch_vccnz .LBB0_1332
	s_mov_b32 s2, 0xc0135761
	v_pk_mul_f32 v[70:71], v[50:51], v[50:51]
	v_pk_mul_f32 v[72:73], v[48:49], v[48:49]
	v_mov_b64_e32 v[74:75], s[2:3]
	s_mov_b32 s2, 0xbdd2d3e8
	v_pk_fma_f32 v[70:71], v[70:71], s[2:3], v[74:75] op_sel_hi:[1,0,0]
	v_pk_fma_f32 v[72:73], v[72:73], s[2:3], v[74:75] op_sel_hi:[1,0,0]
	v_pk_mul_f32 v[70:71], v[50:51], v[70:71]
	v_pk_mul_f32 v[72:73], v[48:49], v[72:73]
	v_exp_f32_e32 v70, v70
	v_exp_f32_e32 v72, v72
	v_exp_f32_e32 v71, v71
	v_exp_f32_e32 v73, v73
	v_pk_add_f32 v[70:71], v[70:71], 1.0 op_sel_hi:[1,0]
	v_pk_add_f32 v[72:73], v[72:73], 1.0 op_sel_hi:[1,0]
	v_rcp_f32_e32 v70, v70
	v_rcp_f32_e32 v72, v72
	v_rcp_f32_e32 v71, v71
	v_rcp_f32_e32 v73, v73
	v_pk_mul_f32 v[50:51], v[50:51], v[70:71]
	v_pk_mul_f32 v[48:49], v[48:49], v[72:73]
.LBB0_1332:
	s_and_b64 vcc, exec, s[4:5]
	v_cvt_pk_bf16_f32 v154, v48, v49
	v_cvt_pk_bf16_f32 v155, v50, v51
	s_nop 1
	v_permlane16_swap_b32_e32 v152, v154
	v_permlane16_swap_b32_e32 v153, v155
	v_lshl_add_u64 v[158:159], v[68:69], 0, v[156:157]
	global_store_dwordx4 v[158:159], v[152:155], off offset:256
	s_nop 1
	s_cbranch_vccnz .LBB0_1336
	v_mov_b32_e32 v68, v62
	v_mov_b32_e32 v69, v60
	v_mov_b32_e32 v70, v63
	v_mov_b32_e32 v71, v60
	v_pk_add_f32 v[72:73], v[68:69], v[70:71]
	v_pk_mul_f32 v[68:69], v[68:69], v[70:71]
	v_mul_f32_e32 v71, v58, v58
	v_mov_b32_e32 v73, v69
	v_pk_add_f32 v[68:69], v[60:61], v[60:61] op_sel:[1,0]
	v_pk_mul_f32 v[60:61], v[60:61], v[60:61]
	v_mov_b32_e32 v70, v58
	v_mov_b32_e32 v69, v61
	v_pk_add_f32 v[60:61], v[68:69], v[72:73]
	v_mul_f32_e32 v68, v62, v62
	v_pk_fma_f32 v[62:63], v[62:63], v[62:63], v[68:69] op_sel_hi:[1,1,0]
	v_mul_f32_e32 v69, v57, v57
	v_mov_b32_e32 v62, v65
	v_pk_add_f32 v[60:61], v[60:61], v[62:63]
	v_mul_f32_e32 v63, v56, v56
	v_mul_f32_e32 v73, v59, v59
	v_mov_b32_e32 v62, v56
	v_mov_b32_e32 v68, v57
	v_mov_b32_e32 v72, v59
	v_pk_add_f32 v[56:57], v[62:63], v[68:69]
	v_pk_add_f32 v[58:59], v[70:71], v[72:73]
	v_mul_f32_e32 v63, v54, v54
	v_pk_add_f32 v[56:57], v[56:57], v[58:59]
	v_mul_f32_e32 v59, v52, v52
	v_pk_add_f32 v[56:57], v[60:61], v[56:57]
	v_mul_f32_e32 v61, v53, v53
	v_mul_f32_e32 v69, v55, v55
	v_mov_b32_e32 v58, v52
	v_mov_b32_e32 v60, v53
	v_mov_b32_e32 v62, v54
	v_mov_b32_e32 v68, v55
	v_pk_add_f32 v[52:53], v[58:59], v[60:61]
	v_pk_add_f32 v[54:55], v[62:63], v[68:69]
	v_cmp_lt_i32_e32 vcc, v206, v204
	v_pk_add_f32 v[52:53], v[52:53], v[54:55]
	v_mul_f32_e32 v55, v48, v48
	v_cndmask_b32_e32 v54, v203, v206, vcc
	v_pk_add_f32 v[52:53], v[56:57], v[52:53]
	v_mul_f32_e32 v57, v49, v49
	v_mul_f32_e32 v59, v50, v50
	v_mul_f32_e32 v61, v51, v51
	v_lshlrev_b32_e32 v62, 2, v54
	v_mov_b32_e32 v54, v48
	v_mov_b32_e32 v56, v49
	v_mov_b32_e32 v58, v50
	v_mov_b32_e32 v60, v51
	v_pk_add_f32 v[48:49], v[54:55], v[56:57]
	v_pk_add_f32 v[50:51], v[58:59], v[60:61]
	v_cmp_lt_i32_e32 vcc, v205, v204
	v_pk_add_f32 v[48:49], v[48:49], v[50:51]
	s_nop 0
	v_pk_add_f32 v[48:49], v[52:53], v[48:49]
	ds_bpermute_b32 v50, v62, v48
	ds_bpermute_b32 v51, v62, v49
	v_cndmask_b32_e32 v52, v203, v205, vcc
	v_lshlrev_b32_e32 v52, 2, v52
	s_waitcnt lgkmcnt(0)
	v_pk_add_f32 v[48:49], v[48:49], v[50:51]
	ds_bpermute_b32 v50, v52, v48
	ds_bpermute_b32 v51, v52, v49
	s_and_saveexec_b64 s[2:3], s[6:7]
	s_cbranch_execz .LBB0_1335
	v_readlane_b32 s8, v249, 5
	v_lshlrev_b64 v[52:53], 7, v[66:67]
	v_readlane_b32 s9, v249, 6
	s_waitcnt lgkmcnt(0)
	v_pk_add_f32 v[48:49], v[48:49], v[50:51]
	v_lshl_add_u64 v[52:53], s[8:9], 0, v[52:53]
	v_lshl_add_u64 v[52:53], s[94:95], 3, v[52:53]
	global_store_dwordx2 v[52:53], v[48:49], off

; __device__ __forceinline__ unsigned cvt_pk_bf16(float lo, float hi) { unsigned r; asm volatile("v_cvt_pk_bf16_f32 %0, %1, %2" : "=v"(r) : "v"(lo), "v"(hi)); return r; }
; __device__ __forceinline__ f32x4 gelu4(const f32x4 x) {
;     const f32x4 t = x * x, a = x * (t * -0.10294324f + -2.3022082f);
;     f32x4 e; e[0] = __builtin_amdgcn_exp2f(a[0]); e[1] = __builtin_amdgcn_exp2f(a[1]); e[2] = __builtin_amdgcn_exp2f(a[2]); e[3] = __builtin_amdgcn_exp2f(a[3]);
;     const f32x4 d = e + 1.0f;
;     f32x4 r; r[0] = __builtin_amdgcn_rcpf(d[0]); r[1] = __builtin_amdgcn_rcpf(d[1]); r[2] = __builtin_amdgcn_rcpf(d[2]); r[3] = __builtin_amdgcn_rcpf(d[3]);
;     return x * r;
; }
;     __device__ __forceinline__ void operator()(const f32x4 (&acc)[2][2][4][2], const Unit& u, int wr, int wc, int fr, int fq) const {
;     ...
;             for (int m = 0; m < 4; ++m) {
;                 const int row = row0 + ai * HALF + m * 16; bf16_t* rowp = proj + (size_t)row * INW + col0; float s = 0.f, q = 0.f;
; #pragma unroll
;                 for (int bj = 0; bj < 2; ++bj)
; #pragma unroll
;                     for (int n = 0; n < 2; ++n) { f32x4 v = acc[ai][bj][m][n];
;                         if (act) v = gelu4(v);
;                         s += (v[0] + v[1]) + (v[2] + v[3]); q += (v[0] * v[0] + v[1] * v[1]) + (v[2] * v[2] + v[3] * v[3]);
;                         u32x2 pk; pk.x = cvt_pk_bf16(v[0], v[1]); pk.y = cvt_pk_bf16(v[2], v[3]); *(u32x2*)(rowp + bj * HALF + n * 16) = pk; }
;                 if (st) { s += __shfl_xor(s, 16); s += __shfl_xor(s, 32); q += __shfl_xor(q, 16); q += __shfl_xor(q, 32);
;                     if (fq == 0) { float* sp = stats + ((size_t)row * 16 + (u.pn - 6) * 4 + wc) * 2; sp[0] = s; sp[1] = q; } }
.LBB0_1338:
	v_add_u32_e32 v48, 0x90, v130
	v_ashrrev_i32_e32 v49, 31, v48
	s_waitcnt lgkmcnt(0)
	v_lshlrev_b64 v[50:51], 13, v[48:49]
	v_lshl_add_u64 v[50:51], s[80:81], 0, v[50:51]
	v_lshl_add_u64 v[50:51], v[50:51], 0, v[64:65]
	s_and_b64 vcc, exec, s[0:1]
	v_cvt_pk_bf16_f32 v152, v44, v45
	v_cvt_pk_bf16_f32 v153, v46, v47
	s_cbranch_vccnz .LBB0_1340
	s_mov_b32 s2, 0xc0135761
	v_pk_mul_f32 v[52:53], v[42:43], v[42:43]
	v_pk_mul_f32 v[54:55], v[40:41], v[40:41]
	v_mov_b64_e32 v[56:57], s[2:3]
	s_mov_b32 s2, 0xbdd2d3e8
	v_pk_fma_f32 v[52:53], v[52:53], s[2:3], v[56:57] op_sel_hi:[1,0,0]
	v_pk_fma_f32 v[54:55], v[54:55], s[2:3], v[56:57] op_sel_hi:[1,0,0]
	v_pk_mul_f32 v[52:53], v[42:43], v[52:53]
	v_pk_mul_f32 v[54:55], v[40:41], v[54:55]
	v_exp_f32_e32 v52, v52
	v_exp_f32_e32 v54, v54
	v_exp_f32_e32 v53, v53
	v_exp_f32_e32 v55, v55
	v_pk_add_f32 v[52:53], v[52:53], 1.0 op_sel_hi:[1,0]
	v_pk_add_f32 v[54:55], v[54:55], 1.0 op_sel_hi:[1,0]
	v_rcp_f32_e32 v52, v52
	v_rcp_f32_e32 v54, v54
	v_rcp_f32_e32 v53, v53
	v_rcp_f32_e32 v55, v55
	v_pk_mul_f32 v[42:43], v[42:43], v[52:53]
	v_pk_mul_f32 v[40:41], v[40:41], v[54:55]
.LBB0_1340:
	s_and_b64 vcc, exec, s[0:1]
	v_cvt_pk_bf16_f32 v154, v40, v41
	v_cvt_pk_bf16_f32 v155, v42, v43
	s_nop 1
	v_permlane16_swap_b32_e32 v152, v154
	v_permlane16_swap_b32_e32 v153, v155
	v_lshl_add_u64 v[158:159], v[50:51], 0, v[156:157]
	global_store_dwordx4 v[158:159], v[152:155], off
	s_nop 1
	s_cbranch_vccnz .LBB0_1342
	s_mov_b32 s2, 0xc0135761
	v_pk_mul_f32 v[52:53], v[38:39], v[38:39]
	v_pk_mul_f32 v[54:55], v[36:37], v[36:37]
	v_mov_b64_e32 v[56:57], s[2:3]
	s_mov_b32 s2, 0xbdd2d3e8
	v_pk_fma_f32 v[52:53], v[52:53], s[2:3], v[56:57] op_sel_hi:[1,0,0]
	v_pk_fma_f32 v[54:55], v[54:55], s[2:3], v[56:57] op_sel_hi:[1,0,0]
	v_pk_mul_f32 v[52:53], v[38:39], v[52:53]
	v_pk_mul_f32 v[54:55], v[36:37], v[54:55]
	v_exp_f32_e32 v52, v52
	v_exp_f32_e32 v54, v54
	v_exp_f32_e32 v53, v53
	v_exp_f32_e32 v55, v55
	v_pk_add_f32 v[52:53], v[52:53], 1.0 op_sel_hi:[1,0]
	v_pk_add_f32 v[54:55], v[54:55], 1.0 op_sel_hi:[1,0]
	v_rcp_f32_e32 v52, v52
	v_rcp_f32_e32 v54, v54
	v_rcp_f32_e32 v53, v53
	v_rcp_f32_e32 v55, v55
	v_pk_mul_f32 v[38:39], v[38:39], v[52:53]
	v_pk_mul_f32 v[36:37], v[36:37], v[54:55]
.LBB0_1342:
	s_and_b64 vcc, exec, s[0:1]
	v_cvt_pk_bf16_f32 v152, v36, v37
	v_cvt_pk_bf16_f32 v153, v38, v39
	s_cbranch_vccnz .LBB0_1344
	s_mov_b32 s2, 0xc0135761
	v_pk_mul_f32 v[52:53], v[34:35], v[34:35]
	v_pk_mul_f32 v[54:55], v[32:33], v[32:33]
	v_mov_b64_e32 v[56:57], s[2:3]
	s_mov_b32 s2, 0xbdd2d3e8
	v_pk_fma_f32 v[52:53], v[52:53], s[2:3], v[56:57] op_sel_hi:[1,0,0]
	v_pk_fma_f32 v[54:55], v[54:55], s[2:3], v[56:57] op_sel_hi:[1,0,0]
	v_pk_mul_f32 v[52:53], v[34:35], v[52:53]
	v_pk_mul_f32 v[54:55], v[32:33], v[54:55]
	v_exp_f32_e32 v52, v52
	v_exp_f32_e32 v54, v54
	v_exp_f32_e32 v53, v53
	v_exp_f32_e32 v55, v55
	v_pk_add_f32 v[52:53], v[52:53], 1.0 op_sel_hi:[1,0]
	v_pk_add_f32 v[54:55], v[54:55], 1.0 op_sel_hi:[1,0]
	v_rcp_f32_e32 v52, v52
	v_rcp_f32_e32 v54, v54
	v_rcp_f32_e32 v53, v53
	v_rcp_f32_e32 v55, v55
	v_pk_mul_f32 v[34:35], v[34:35], v[52:53]
	v_pk_mul_f32 v[32:33], v[32:33], v[54:55]
.LBB0_1344:
	s_and_b64 vcc, exec, s[4:5]
	v_cvt_pk_bf16_f32 v154, v32, v33
	v_cvt_pk_bf16_f32 v155, v34, v35
	s_nop 1
	v_permlane16_swap_b32_e32 v152, v154
	v_permlane16_swap_b32_e32 v153, v155
	v_lshl_add_u64 v[158:159], v[50:51], 0, v[156:157]
	global_store_dwordx4 v[158:159], v[152:155], off offset:256
	s_nop 1
	s_cbranch_vccnz .LBB0_1348
	v_mov_b32_e32 v50, v46
	v_mov_b32_e32 v51, v44
	v_mov_b32_e32 v52, v47
	v_mov_b32_e32 v53, v44
	v_pk_add_f32 v[54:55], v[50:51], v[52:53]
	v_pk_mul_f32 v[50:51], v[50:51], v[52:53]
	v_mul_f32_e32 v53, v42, v42
	v_mov_b32_e32 v55, v51
	v_pk_add_f32 v[50:51], v[44:45], v[44:45] op_sel:[1,0]
	v_pk_mul_f32 v[44:45], v[44:45], v[44:45]
	v_mov_b32_e32 v52, v42
	v_mov_b32_e32 v51, v45
	v_pk_add_f32 v[44:45], v[50:51], v[54:55]
	v_mul_f32_e32 v50, v46, v46
	v_pk_fma_f32 v[46:47], v[46:47], v[46:47], v[50:51] op_sel_hi:[1,1,0]
	v_mul_f32_e32 v51, v41, v41
	v_mov_b32_e32 v46, v65
	v_pk_add_f32 v[44:45], v[44:45], v[46:47]
	v_mul_f32_e32 v47, v40, v40
	v_mul_f32_e32 v55, v43, v43
	v_mov_b32_e32 v46, v40
	v_mov_b32_e32 v50, v41
	v_mov_b32_e32 v54, v43
	v_pk_add_f32 v[40:41], v[46:47], v[50:51]
	v_pk_add_f32 v[42:43], v[52:53], v[54:55]
	v_mul_f32_e32 v47, v38, v38
	v_pk_add_f32 v[40:41], v[40:41], v[42:43]
	v_mul_f32_e32 v43, v36, v36
	v_pk_add_f32 v[40:41], v[44:45], v[40:41]
	v_mul_f32_e32 v45, v37, v37
	v_mul_f32_e32 v51, v39, v39
	v_mov_b32_e32 v42, v36
	v_mov_b32_e32 v44, v37
	v_mov_b32_e32 v46, v38
	v_mov_b32_e32 v50, v39
	v_pk_add_f32 v[36:37], v[42:43], v[44:45]
	v_pk_add_f32 v[38:39], v[46:47], v[50:51]
	v_cmp_lt_i32_e32 vcc, v206, v204
	v_pk_add_f32 v[36:37], v[36:37], v[38:39]
	v_mul_f32_e32 v39, v32, v32
	v_cndmask_b32_e32 v38, v203, v206, vcc
	v_pk_add_f32 v[36:37], v[40:41], v[36:37]
	v_mul_f32_e32 v41, v33, v33
	v_mul_f32_e32 v43, v34, v34
	v_mul_f32_e32 v45, v35, v35
	v_lshlrev_b32_e32 v46, 2, v38
	v_mov_b32_e32 v38, v32
	v_mov_b32_e32 v40, v33
	v_mov_b32_e32 v42, v34
	v_mov_b32_e32 v44, v35
	v_pk_add_f32 v[32:33], v[38:39], v[40:41]
	v_pk_add_f32 v[34:35], v[42:43], v[44:45]
	v_cmp_lt_i32_e32 vcc, v205, v204
	v_pk_add_f32 v[32:33], v[32:33], v[34:35]
	s_nop 0
	v_pk_add_f32 v[32:33], v[36:37], v[32:33]
	ds_bpermute_b32 v34, v46, v32
	ds_bpermute_b32 v35, v46, v33
	v_cndmask_b32_e32 v36, v203, v205, vcc
	v_lshlrev_b32_e32 v36, 2, v36
	s_waitcnt lgkmcnt(0)
	v_pk_add_f32 v[32:33], v[32:33], v[34:35]
	ds_bpermute_b32 v34, v36, v32
	ds_bpermute_b32 v35, v36, v33
	s_and_saveexec_b64 s[2:3], s[6:7]
	s_cbranch_execz .LBB0_1347
	v_readlane_b32 s8, v249, 5
	v_lshlrev_b64 v[36:37], 7, v[48:49]
	v_readlane_b32 s9, v249, 6
	s_waitcnt lgkmcnt(0)
	v_pk_add_f32 v[32:33], v[32:33], v[34:35]
	v_lshl_add_u64 v[36:37], s[8:9], 0, v[36:37]
	v_lshl_add_u64 v[36:37], s[94:95], 3, v[36:37]
	global_store_dwordx2 v[36:37], v[32:33], off

; __device__ __forceinline__ unsigned cvt_pk_bf16(float lo, float hi) { unsigned r; asm volatile("v_cvt_pk_bf16_f32 %0, %1, %2" : "=v"(r) : "v"(lo), "v"(hi)); return r; }
; __device__ __forceinline__ f32x4 gelu4(const f32x4 x) {
;     const f32x4 t = x * x, a = x * (t * -0.10294324f + -2.3022082f);
;     f32x4 e; e[0] = __builtin_amdgcn_exp2f(a[0]); e[1] = __builtin_amdgcn_exp2f(a[1]); e[2] = __builtin_amdgcn_exp2f(a[2]); e[3] = __builtin_amdgcn_exp2f(a[3]);
;     const f32x4 d = e + 1.0f;
;     f32x4 r; r[0] = __builtin_amdgcn_rcpf(d[0]); r[1] = __builtin_amdgcn_rcpf(d[1]); r[2] = __builtin_amdgcn_rcpf(d[2]); r[3] = __builtin_amdgcn_rcpf(d[3]);
;     return x * r;
; }
;     __device__ __forceinline__ void operator()(const f32x4 (&acc)[2][2][4][2], const Unit& u, int wr, int wc, int fr, int fq) const {
;     ...
;             for (int m = 0; m < 4; ++m) {
;                 const int row = row0 + ai * HALF + m * 16; bf16_t* rowp = proj + (size_t)row * INW + col0; float s = 0.f, q = 0.f;
; #pragma unroll
;                 for (int bj = 0; bj < 2; ++bj)
; #pragma unroll
;                     for (int n = 0; n < 2; ++n) { f32x4 v = acc[ai][bj][m][n];
;                         if (act) v = gelu4(v);
;                         s += (v[0] + v[1]) + (v[2] + v[3]); q += (v[0] * v[0] + v[1] * v[1]) + (v[2] * v[2] + v[3] * v[3]);
;                         u32x2 pk; pk.x = cvt_pk_bf16(v[0], v[1]); pk.y = cvt_pk_bf16(v[2], v[3]); *(u32x2*)(rowp + bj * HALF + n * 16) = pk; }
;                 if (st) { s += __shfl_xor(s, 16); s += __shfl_xor(s, 32); q += __shfl_xor(q, 16); q += __shfl_xor(q, 32);
;                     if (fq == 0) { float* sp = stats + ((size_t)row * 16 + (u.pn - 6) * 4 + wc) * 2; sp[0] = s; sp[1] = q; } }
.LBB0_1350:
	v_add_u32_e32 v32, 0xa0, v130
	v_ashrrev_i32_e32 v33, 31, v32
	s_waitcnt lgkmcnt(0)
	v_lshlrev_b64 v[34:35], 13, v[32:33]
	v_lshl_add_u64 v[34:35], s[80:81], 0, v[34:35]
	v_lshl_add_u64 v[34:35], v[34:35], 0, v[64:65]
	s_and_b64 vcc, exec, s[0:1]
	v_cvt_pk_bf16_f32 v152, v28, v29
	v_cvt_pk_bf16_f32 v153, v30, v31
	s_cbranch_vccnz .LBB0_1352
	s_mov_b32 s2, 0xc0135761
	v_pk_mul_f32 v[36:37], v[26:27], v[26:27]
	v_pk_mul_f32 v[38:39], v[24:25], v[24:25]
	v_mov_b64_e32 v[40:41], s[2:3]
	s_mov_b32 s2, 0xbdd2d3e8
	v_pk_fma_f32 v[36:37], v[36:37], s[2:3], v[40:41] op_sel_hi:[1,0,0]
	v_pk_fma_f32 v[38:39], v[38:39], s[2:3], v[40:41] op_sel_hi:[1,0,0]
	v_pk_mul_f32 v[36:37], v[26:27], v[36:37]
	v_pk_mul_f32 v[38:39], v[24:25], v[38:39]
	v_exp_f32_e32 v36, v36
	v_exp_f32_e32 v38, v38
	v_exp_f32_e32 v37, v37
	v_exp_f32_e32 v39, v39
	v_pk_add_f32 v[36:37], v[36:37], 1.0 op_sel_hi:[1,0]
	v_pk_add_f32 v[38:39], v[38:39], 1.0 op_sel_hi:[1,0]
	v_rcp_f32_e32 v36, v36
	v_rcp_f32_e32 v38, v38
	v_rcp_f32_e32 v37, v37
	v_rcp_f32_e32 v39, v39
	v_pk_mul_f32 v[26:27], v[26:27], v[36:37]
	v_pk_mul_f32 v[24:25], v[24:25], v[38:39]
.LBB0_1352:
	s_and_b64 vcc, exec, s[0:1]
	v_cvt_pk_bf16_f32 v154, v24, v25
	v_cvt_pk_bf16_f32 v155, v26, v27
	s_nop 1
	v_permlane16_swap_b32_e32 v152, v154
	v_permlane16_swap_b32_e32 v153, v155
	v_lshl_add_u64 v[158:159], v[34:35], 0, v[156:157]
	global_store_dwordx4 v[158:159], v[152:155], off
	s_nop 1
	s_cbranch_vccnz .LBB0_1354
	s_mov_b32 s2, 0xc0135761
	v_pk_mul_f32 v[36:37], v[22:23], v[22:23]
	v_pk_mul_f32 v[38:39], v[20:21], v[20:21]
	v_mov_b64_e32 v[40:41], s[2:3]
	s_mov_b32 s2, 0xbdd2d3e8
	v_pk_fma_f32 v[36:37], v[36:37], s[2:3], v[40:41] op_sel_hi:[1,0,0]
	v_pk_fma_f32 v[38:39], v[38:39], s[2:3], v[40:41] op_sel_hi:[1,0,0]
	v_pk_mul_f32 v[36:37], v[22:23], v[36:37]
	v_pk_mul_f32 v[38:39], v[20:21], v[38:39]
	v_exp_f32_e32 v36, v36
	v_exp_f32_e32 v38, v38
	v_exp_f32_e32 v37, v37
	v_exp_f32_e32 v39, v39
	v_pk_add_f32 v[36:37], v[36:37], 1.0 op_sel_hi:[1,0]
	v_pk_add_f32 v[38:39], v[38:39], 1.0 op_sel_hi:[1,0]
	v_rcp_f32_e32 v36, v36
	v_rcp_f32_e32 v38, v38
	v_rcp_f32_e32 v37, v37
	v_rcp_f32_e32 v39, v39
	v_pk_mul_f32 v[22:23], v[22:23], v[36:37]
	v_pk_mul_f32 v[20:21], v[20:21], v[38:39]
.LBB0_1354:
	s_and_b64 vcc, exec, s[0:1]
	v_cvt_pk_bf16_f32 v152, v20, v21
	v_cvt_pk_bf16_f32 v153, v22, v23
	s_cbranch_vccnz .LBB0_1356
	s_mov_b32 s2, 0xc0135761
	v_pk_mul_f32 v[36:37], v[18:19], v[18:19]
	v_pk_mul_f32 v[38:39], v[16:17], v[16:17]
	v_mov_b64_e32 v[40:41], s[2:3]
	s_mov_b32 s2, 0xbdd2d3e8
	v_pk_fma_f32 v[36:37], v[36:37], s[2:3], v[40:41] op_sel_hi:[1,0,0]
	v_pk_fma_f32 v[38:39], v[38:39], s[2:3], v[40:41] op_sel_hi:[1,0,0]
	v_pk_mul_f32 v[36:37], v[18:19], v[36:37]
	v_pk_mul_f32 v[38:39], v[16:17], v[38:39]
	v_exp_f32_e32 v36, v36
	v_exp_f32_e32 v38, v38
	v_exp_f32_e32 v37, v37
	v_exp_f32_e32 v39, v39
	v_pk_add_f32 v[36:37], v[36:37], 1.0 op_sel_hi:[1,0]
	v_pk_add_f32 v[38:39], v[38:39], 1.0 op_sel_hi:[1,0]
	v_rcp_f32_e32 v36, v36
	v_rcp_f32_e32 v38, v38
	v_rcp_f32_e32 v37, v37
	v_rcp_f32_e32 v39, v39
	v_pk_mul_f32 v[18:19], v[18:19], v[36:37]
	v_pk_mul_f32 v[16:17], v[16:17], v[38:39]
.LBB0_1356:
	s_and_b64 vcc, exec, s[4:5]
	v_cvt_pk_bf16_f32 v154, v16, v17
	v_cvt_pk_bf16_f32 v155, v18, v19
	s_nop 1
	v_permlane16_swap_b32_e32 v152, v154
	v_permlane16_swap_b32_e32 v153, v155
	v_lshl_add_u64 v[158:159], v[34:35], 0, v[156:157]
	global_store_dwordx4 v[158:159], v[152:155], off offset:256
	s_nop 1
	s_cbranch_vccnz .LBB0_1360
	v_mov_b32_e32 v34, v30
	v_mov_b32_e32 v35, v28
	v_mov_b32_e32 v36, v31
	v_mov_b32_e32 v37, v28
	v_pk_add_f32 v[38:39], v[34:35], v[36:37]
	v_pk_mul_f32 v[34:35], v[34:35], v[36:37]
	v_mul_f32_e32 v37, v26, v26
	v_mov_b32_e32 v39, v35
	v_pk_add_f32 v[34:35], v[28:29], v[28:29] op_sel:[1,0]
	v_pk_mul_f32 v[28:29], v[28:29], v[28:29]
	v_mov_b32_e32 v36, v26
	v_mov_b32_e32 v35, v29
	v_pk_add_f32 v[28:29], v[34:35], v[38:39]
	v_mul_f32_e32 v34, v30, v30
	v_pk_fma_f32 v[30:31], v[30:31], v[30:31], v[34:35] op_sel_hi:[1,1,0]
	v_mul_f32_e32 v35, v25, v25
	v_mov_b32_e32 v30, v65
	v_pk_add_f32 v[28:29], v[28:29], v[30:31]
	v_mul_f32_e32 v31, v24, v24
	v_mul_f32_e32 v39, v27, v27
	v_mov_b32_e32 v30, v24
	v_mov_b32_e32 v34, v25
	v_mov_b32_e32 v38, v27
	v_pk_add_f32 v[24:25], v[30:31], v[34:35]
	v_pk_add_f32 v[26:27], v[36:37], v[38:39]
	v_mul_f32_e32 v31, v22, v22
	v_pk_add_f32 v[24:25], v[24:25], v[26:27]
	v_mul_f32_e32 v27, v20, v20
	v_pk_add_f32 v[24:25], v[28:29], v[24:25]
	v_mul_f32_e32 v29, v21, v21
	v_mul_f32_e32 v35, v23, v23
	v_mov_b32_e32 v26, v20
	v_mov_b32_e32 v28, v21
	v_mov_b32_e32 v30, v22
	v_mov_b32_e32 v34, v23
	v_pk_add_f32 v[20:21], v[26:27], v[28:29]
	v_pk_add_f32 v[22:23], v[30:31], v[34:35]
	v_cmp_lt_i32_e32 vcc, v206, v204
	v_pk_add_f32 v[20:21], v[20:21], v[22:23]
	v_mul_f32_e32 v23, v16, v16
	v_cndmask_b32_e32 v22, v203, v206, vcc
	v_pk_add_f32 v[20:21], v[24:25], v[20:21]
	v_mul_f32_e32 v25, v17, v17
	v_mul_f32_e32 v27, v18, v18
	v_mul_f32_e32 v29, v19, v19
	v_lshlrev_b32_e32 v30, 2, v22
	v_mov_b32_e32 v22, v16
	v_mov_b32_e32 v24, v17
	v_mov_b32_e32 v26, v18
	v_mov_b32_e32 v28, v19
	v_pk_add_f32 v[16:17], v[22:23], v[24:25]
	v_pk_add_f32 v[18:19], v[26:27], v[28:29]
	v_cmp_lt_i32_e32 vcc, v205, v204
	v_pk_add_f32 v[16:17], v[16:17], v[18:19]
	s_nop 0
	v_pk_add_f32 v[16:17], v[20:21], v[16:17]
	ds_bpermute_b32 v18, v30, v16
	ds_bpermute_b32 v19, v30, v17
	v_cndmask_b32_e32 v20, v203, v205, vcc
	v_lshlrev_b32_e32 v20, 2, v20
	s_waitcnt lgkmcnt(0)
	v_pk_add_f32 v[16:17], v[16:17], v[18:19]
	ds_bpermute_b32 v18, v20, v16
	ds_bpermute_b32 v19, v20, v17
	s_and_saveexec_b64 s[2:3], s[6:7]
	s_cbranch_execz .LBB0_1359
	v_readlane_b32 s8, v249, 5
	v_lshlrev_b64 v[20:21], 7, v[32:33]
	v_readlane_b32 s9, v249, 6
	s_waitcnt lgkmcnt(0)
	v_pk_add_f32 v[16:17], v[16:17], v[18:19]
	v_lshl_add_u64 v[20:21], s[8:9], 0, v[20:21]
	v_lshl_add_u64 v[20:21], s[94:95], 3, v[20:21]
	global_store_dwordx2 v[20:21], v[16:17], off

; __device__ __forceinline__ unsigned cvt_pk_bf16(float lo, float hi) { unsigned r; asm volatile("v_cvt_pk_bf16_f32 %0, %1, %2" : "=v"(r) : "v"(lo), "v"(hi)); return r; }
; __device__ __forceinline__ f32x4 gelu4(const f32x4 x) {
;     const f32x4 t = x * x, a = x * (t * -0.10294324f + -2.3022082f);
;     f32x4 e; e[0] = __builtin_amdgcn_exp2f(a[0]); e[1] = __builtin_amdgcn_exp2f(a[1]); e[2] = __builtin_amdgcn_exp2f(a[2]); e[3] = __builtin_amdgcn_exp2f(a[3]);
;     const f32x4 d = e + 1.0f;
;     f32x4 r; r[0] = __builtin_amdgcn_rcpf(d[0]); r[1] = __builtin_amdgcn_rcpf(d[1]); r[2] = __builtin_amdgcn_rcpf(d[2]); r[3] = __builtin_amdgcn_rcpf(d[3]);
;     return x * r;
; }
;     __device__ __forceinline__ void operator()(const f32x4 (&acc)[2][2][4][2], const Unit& u, int wr, int wc, int fr, int fq) const {
;     ...
;             for (int m = 0; m < 4; ++m) {
;                 const int row = row0 + ai * HALF + m * 16; bf16_t* rowp = proj + (size_t)row * INW + col0; float s = 0.f, q = 0.f;
; #pragma unroll
;                 for (int bj = 0; bj < 2; ++bj)
; #pragma unroll
;                     for (int n = 0; n < 2; ++n) { f32x4 v = acc[ai][bj][m][n];
;                         if (act) v = gelu4(v);
;                         s += (v[0] + v[1]) + (v[2] + v[3]); q += (v[0] * v[0] + v[1] * v[1]) + (v[2] * v[2] + v[3] * v[3]);
;                         u32x2 pk; pk.x = cvt_pk_bf16(v[0], v[1]); pk.y = cvt_pk_bf16(v[2], v[3]); *(u32x2*)(rowp + bj * HALF + n * 16) = pk; }
;                 if (st) { s += __shfl_xor(s, 16); s += __shfl_xor(s, 32); q += __shfl_xor(q, 16); q += __shfl_xor(q, 32);
;                     if (fq == 0) { float* sp = stats + ((size_t)row * 16 + (u.pn - 6) * 4 + wc) * 2; sp[0] = s; sp[1] = q; } }
.LBB0_1362:
	v_add_u32_e32 v16, 0xb0, v130
	v_ashrrev_i32_e32 v17, 31, v16
	s_waitcnt lgkmcnt(0)
	v_lshlrev_b64 v[18:19], 13, v[16:17]
	v_lshl_add_u64 v[18:19], s[80:81], 0, v[18:19]
	v_lshl_add_u64 v[18:19], v[18:19], 0, v[64:65]
	s_and_b64 vcc, exec, s[0:1]
	v_cvt_pk_bf16_f32 v152, v12, v13
	v_cvt_pk_bf16_f32 v153, v14, v15
	s_cbranch_vccnz .LBB0_1364
	s_mov_b32 s2, 0xc0135761
	v_pk_mul_f32 v[20:21], v[10:11], v[10:11]
	v_pk_mul_f32 v[22:23], v[8:9], v[8:9]
	v_mov_b64_e32 v[24:25], s[2:3]
	s_mov_b32 s2, 0xbdd2d3e8
	v_pk_fma_f32 v[20:21], v[20:21], s[2:3], v[24:25] op_sel_hi:[1,0,0]
	v_pk_fma_f32 v[22:23], v[22:23], s[2:3], v[24:25] op_sel_hi:[1,0,0]
	v_pk_mul_f32 v[20:21], v[10:11], v[20:21]
	v_pk_mul_f32 v[22:23], v[8:9], v[22:23]
	v_exp_f32_e32 v20, v20
	v_exp_f32_e32 v22, v22
	v_exp_f32_e32 v21, v21
	v_exp_f32_e32 v23, v23
	v_pk_add_f32 v[20:21], v[20:21], 1.0 op_sel_hi:[1,0]
	v_pk_add_f32 v[22:23], v[22:23], 1.0 op_sel_hi:[1,0]
	v_rcp_f32_e32 v20, v20
	v_rcp_f32_e32 v22, v22
	v_rcp_f32_e32 v21, v21
	v_rcp_f32_e32 v23, v23
	v_pk_mul_f32 v[10:11], v[10:11], v[20:21]
	v_pk_mul_f32 v[8:9], v[8:9], v[22:23]
.LBB0_1364:
	s_and_b64 vcc, exec, s[0:1]
	v_cvt_pk_bf16_f32 v154, v8, v9
	v_cvt_pk_bf16_f32 v155, v10, v11
	s_nop 1
	v_permlane16_swap_b32_e32 v152, v154
	v_permlane16_swap_b32_e32 v153, v155
	v_lshl_add_u64 v[158:159], v[18:19], 0, v[156:157]
	global_store_dwordx4 v[158:159], v[152:155], off
	s_nop 1
	s_cbranch_vccnz .LBB0_1366
	s_mov_b32 s2, 0xc0135761
	v_pk_mul_f32 v[20:21], v[6:7], v[6:7]
	v_pk_mul_f32 v[22:23], v[4:5], v[4:5]
	v_mov_b64_e32 v[24:25], s[2:3]
	s_mov_b32 s2, 0xbdd2d3e8
	v_pk_fma_f32 v[20:21], v[20:21], s[2:3], v[24:25] op_sel_hi:[1,0,0]
	v_pk_fma_f32 v[22:23], v[22:23], s[2:3], v[24:25] op_sel_hi:[1,0,0]
	v_pk_mul_f32 v[20:21], v[6:7], v[20:21]
	v_pk_mul_f32 v[22:23], v[4:5], v[22:23]
	v_exp_f32_e32 v20, v20
	v_exp_f32_e32 v22, v22
	v_exp_f32_e32 v21, v21
	v_exp_f32_e32 v23, v23
	v_pk_add_f32 v[20:21], v[20:21], 1.0 op_sel_hi:[1,0]
	v_pk_add_f32 v[22:23], v[22:23], 1.0 op_sel_hi:[1,0]
	v_rcp_f32_e32 v20, v20
	v_rcp_f32_e32 v22, v22
	v_rcp_f32_e32 v21, v21
	v_rcp_f32_e32 v23, v23
	v_pk_mul_f32 v[6:7], v[6:7], v[20:21]
	v_pk_mul_f32 v[4:5], v[4:5], v[22:23]
.LBB0_1366:
	s_and_b64 vcc, exec, s[0:1]
	v_cvt_pk_bf16_f32 v152, v4, v5
	v_cvt_pk_bf16_f32 v153, v6, v7
	s_cbranch_vccnz .LBB0_1368
	s_mov_b32 s0, 0xc0135761
	v_pk_mul_f32 v[20:21], v[2:3], v[2:3]
	v_pk_mul_f32 v[22:23], v[0:1], v[0:1]
	v_mov_b64_e32 v[24:25], s[0:1]
	s_mov_b32 s0, 0xbdd2d3e8
	v_pk_fma_f32 v[20:21], v[20:21], s[0:1], v[24:25] op_sel_hi:[1,0,0]
	v_pk_fma_f32 v[22:23], v[22:23], s[0:1], v[24:25] op_sel_hi:[1,0,0]
	v_pk_mul_f32 v[20:21], v[2:3], v[20:21]
	v_pk_mul_f32 v[22:23], v[0:1], v[22:23]
	v_exp_f32_e32 v20, v20
	v_exp_f32_e32 v22, v22
	v_exp_f32_e32 v21, v21
	v_exp_f32_e32 v23, v23
	v_pk_add_f32 v[20:21], v[20:21], 1.0 op_sel_hi:[1,0]
	v_pk_add_f32 v[22:23], v[22:23], 1.0 op_sel_hi:[1,0]
	v_rcp_f32_e32 v20, v20
	v_rcp_f32_e32 v22, v22
	v_rcp_f32_e32 v21, v21
	v_rcp_f32_e32 v23, v23
	v_pk_mul_f32 v[2:3], v[2:3], v[20:21]
	v_pk_mul_f32 v[0:1], v[0:1], v[22:23]
.LBB0_1368:
	s_and_b64 vcc, exec, s[4:5]
	v_cvt_pk_bf16_f32 v154, v0, v1
	v_cvt_pk_bf16_f32 v155, v2, v3
	s_nop 1
	v_permlane16_swap_b32_e32 v152, v154
	v_permlane16_swap_b32_e32 v153, v155
	v_lshl_add_u64 v[158:159], v[18:19], 0, v[156:157]
	global_store_dwordx4 v[158:159], v[152:155], off offset:256
	s_nop 1
	s_cbranch_vccnz .LBB0_1372
	v_mov_b32_e32 v18, v14
	v_mov_b32_e32 v19, v12
	v_mov_b32_e32 v20, v15
	v_mov_b32_e32 v21, v12
	v_pk_add_f32 v[22:23], v[18:19], v[20:21]
	v_pk_mul_f32 v[18:19], v[18:19], v[20:21]
	v_mul_f32_e32 v21, v10, v10
	v_mov_b32_e32 v23, v19
	v_pk_add_f32 v[18:19], v[12:13], v[12:13] op_sel:[1,0]
	v_pk_mul_f32 v[12:13], v[12:13], v[12:13]
	v_mov_b32_e32 v20, v10
	v_mov_b32_e32 v19, v13
	v_pk_add_f32 v[12:13], v[18:19], v[22:23]
	v_mul_f32_e32 v18, v14, v14
	v_pk_fma_f32 v[14:15], v[14:15], v[14:15], v[18:19] op_sel_hi:[1,1,0]
	v_mul_f32_e32 v19, v9, v9
	v_mov_b32_e32 v14, v65
	v_pk_add_f32 v[12:13], v[12:13], v[14:15]
	v_mul_f32_e32 v15, v8, v8
	v_mul_f32_e32 v23, v11, v11
	v_mov_b32_e32 v14, v8
	v_mov_b32_e32 v18, v9
	v_mov_b32_e32 v22, v11
	v_pk_add_f32 v[8:9], v[14:15], v[18:19]
	v_pk_add_f32 v[10:11], v[20:21], v[22:23]
	v_mul_f32_e32 v15, v6, v6
	v_pk_add_f32 v[8:9], v[8:9], v[10:11]
	v_mul_f32_e32 v11, v4, v4
	v_pk_add_f32 v[8:9], v[12:13], v[8:9]
	v_mul_f32_e32 v13, v5, v5
	v_mul_f32_e32 v19, v7, v7
	v_mov_b32_e32 v10, v4
	v_mov_b32_e32 v12, v5
	v_mov_b32_e32 v14, v6
	v_mov_b32_e32 v18, v7
	v_pk_add_f32 v[4:5], v[10:11], v[12:13]
	v_pk_add_f32 v[6:7], v[14:15], v[18:19]
	v_cmp_lt_i32_e32 vcc, v206, v204
	v_pk_add_f32 v[4:5], v[4:5], v[6:7]
	v_mul_f32_e32 v7, v0, v0
	v_cndmask_b32_e32 v6, v203, v206, vcc
	v_pk_add_f32 v[4:5], v[8:9], v[4:5]
	v_mul_f32_e32 v9, v1, v1
	v_mul_f32_e32 v11, v2, v2
	v_mul_f32_e32 v13, v3, v3
	v_lshlrev_b32_e32 v14, 2, v6
	v_mov_b32_e32 v6, v0
	v_mov_b32_e32 v8, v1
	v_mov_b32_e32 v10, v2
	v_mov_b32_e32 v12, v3
	v_pk_add_f32 v[0:1], v[6:7], v[8:9]
	v_pk_add_f32 v[2:3], v[10:11], v[12:13]
	v_cmp_lt_i32_e32 vcc, v205, v204
	v_pk_add_f32 v[0:1], v[0:1], v[2:3]
	s_nop 0
	v_pk_add_f32 v[0:1], v[4:5], v[0:1]
	ds_bpermute_b32 v2, v14, v0
	ds_bpermute_b32 v3, v14, v1
	v_cndmask_b32_e32 v4, v203, v205, vcc
	v_lshlrev_b32_e32 v4, 2, v4
	s_waitcnt lgkmcnt(0)
	v_pk_add_f32 v[0:1], v[0:1], v[2:3]
	ds_bpermute_b32 v2, v4, v0
	ds_bpermute_b32 v3, v4, v1
	s_and_saveexec_b64 s[0:1], s[6:7]
	s_cbranch_execz .LBB0_1371
	v_readlane_b32 s2, v249, 5
	v_lshlrev_b64 v[4:5], 7, v[16:17]
	v_readlane_b32 s3, v249, 6
	s_waitcnt lgkmcnt(0)
	v_pk_add_f32 v[0:1], v[0:1], v[2:3]
	v_lshl_add_u64 v[4:5], s[2:3], 0, v[4:5]
	v_lshl_add_u64 v[4:5], s[94:95], 3, v[4:5]
	global_store_dwordx2 v[4:5], v[0:1], off

; __device__ __forceinline__ unsigned cvt_pk_bf16(float lo, float hi) { unsigned r; asm volatile("v_cvt_pk_bf16_f32 %0, %1, %2" : "=v"(r) : "v"(lo), "v"(hi)); return r; }
; __device__ __forceinline__ f32x4 gelu4(const f32x4 x) {
;     const f32x4 t = x * x, a = x * (t * -0.10294324f + -2.3022082f);
;     f32x4 e; e[0] = __builtin_amdgcn_exp2f(a[0]); e[1] = __builtin_amdgcn_exp2f(a[1]); e[2] = __builtin_amdgcn_exp2f(a[2]); e[3] = __builtin_amdgcn_exp2f(a[3]);
;     const f32x4 d = e + 1.0f;
;     f32x4 r; r[0] = __builtin_amdgcn_rcpf(d[0]); r[1] = __builtin_amdgcn_rcpf(d[1]); r[2] = __builtin_amdgcn_rcpf(d[2]); r[3] = __builtin_amdgcn_rcpf(d[3]);
;     return x * r;
; }
;     __device__ __forceinline__ void operator()(const f32x4 (&acc)[2][2][4][2], const Unit& u, int wr, int wc, int fr, int fq) const {
;         const int row0 = u.pm * BM + wr * 64 + fr, col0 = u.pn * BM + wc * 32 + 4 * fq;
;         const bool act = (u.pn >= 2) && (u.pn < 10), st = (u.pn >= 6) && (u.pn < 10);
; #pragma unroll
;         for (int ai = 0; ai < 2; ++ai)
; #pragma unroll
;             for (int m = 0; m < 4; ++m) {
;                 const int row = row0 + ai * HALF + m * 16; bf16_t* rowp = proj + (size_t)row * INW + col0; float s = 0.f, q = 0.f;
; #pragma unroll
;                 for (int bj = 0; bj < 2; ++bj)
; #pragma unroll
;                     for (int n = 0; n < 2; ++n) { f32x4 v = acc[ai][bj][m][n];
;                         if (act) v = gelu4(v);
;                         s += (v[0] + v[1]) + (v[2] + v[3]); q += (v[0] * v[0] + v[1] * v[1]) + (v[2] * v[2] + v[3] * v[3]);
;                         u32x2 pk; pk.x = cvt_pk_bf16(v[0], v[1]); pk.y = cvt_pk_bf16(v[2], v[3]); *(u32x2*)(rowp + bj * HALF + n * 16) = pk; }
;                 if (st) { s += __shfl_xor(s, 16); s += __shfl_xor(s, 32); q += __shfl_xor(q, 16); q += __shfl_xor(q, 32);
;                     if (fq == 0) { float* sp = stats + ((size_t)row * 16 + (u.pn - 6) * 4 + wc) * 2; sp[0] = s; sp[1] = q; } }
.LBB0_1445:
	v_bfe_u32 v156, v200, 4, 1
	v_mul_u32_u24_e32 v156, 24, v156
	v_mov_b32_e32 v157, 0
	v_lshl_add_u32 v138, s39, 8, v142
	v_ashrrev_i32_e32 v139, 31, v138
	v_lshl_or_b32 v136, s38, 8, v144
	v_lshlrev_b64 v[140:141], 13, v[138:139]
	v_ashrrev_i32_e32 v137, 31, v136
	v_lshl_add_u64 v[140:141], s[80:81], 0, v[140:141]
	v_lshl_add_u64 v[140:141], v[136:137], 1, v[140:141]
	v_cvt_pk_bf16_f32 v152, v126, v127
	v_cvt_pk_bf16_f32 v153, v128, v129
	v_cndmask_b32_e64 v146, 0, 1, s[2:3]
	v_cmp_ne_u32_e64 s[0:1], 1, v146
	s_andn2_b64 vcc, exec, s[2:3]
	s_cbranch_vccnz .LBB0_1447
	v_pk_mul_f32 v[146:147], v[124:125], v[124:125]
	v_pk_mul_f32 v[148:149], v[122:123], v[122:123]
	v_mov_b64_e32 v[150:151], s[40:41]
	s_mov_b32 s2, 0xbdd2d3e8
	v_pk_fma_f32 v[146:147], v[146:147], s[2:3], v[150:151] op_sel_hi:[1,0,0]
	v_pk_fma_f32 v[148:149], v[148:149], s[2:3], v[150:151] op_sel_hi:[1,0,0]
	v_pk_mul_f32 v[146:147], v[124:125], v[146:147]
	v_pk_mul_f32 v[148:149], v[122:123], v[148:149]
	v_exp_f32_e32 v146, v146
	v_exp_f32_e32 v148, v148
	v_exp_f32_e32 v147, v147
	v_exp_f32_e32 v149, v149
	v_pk_add_f32 v[146:147], v[146:147], 1.0 op_sel_hi:[1,0]
	v_pk_add_f32 v[148:149], v[148:149], 1.0 op_sel_hi:[1,0]
	v_rcp_f32_e32 v146, v146
	v_rcp_f32_e32 v148, v148
	v_rcp_f32_e32 v147, v147
	v_rcp_f32_e32 v149, v149
	v_pk_mul_f32 v[124:125], v[124:125], v[146:147]
	v_pk_mul_f32 v[122:123], v[122:123], v[148:149]
.LBB0_1447:
	s_and_b64 vcc, exec, s[0:1]
	v_cvt_pk_bf16_f32 v154, v122, v123
	v_cvt_pk_bf16_f32 v155, v124, v125
	s_nop 1
	v_permlane16_swap_b32_e32 v152, v154
	v_permlane16_swap_b32_e32 v153, v155
	v_lshl_add_u64 v[158:159], v[140:141], 0, v[156:157]
	global_store_dwordx4 v[158:159], v[152:155], off
	s_nop 1
	s_cbranch_vccnz .LBB0_1449
	v_pk_mul_f32 v[146:147], v[120:121], v[120:121]
	v_pk_mul_f32 v[148:149], v[118:119], v[118:119]
	v_mov_b64_e32 v[150:151], s[40:41]
	s_mov_b32 s2, 0xbdd2d3e8
	v_pk_fma_f32 v[146:147], v[146:147], s[2:3], v[150:151] op_sel_hi:[1,0,0]
	v_pk_fma_f32 v[148:149], v[148:149], s[2:3], v[150:151] op_sel_hi:[1,0,0]
	v_pk_mul_f32 v[146:147], v[120:121], v[146:147]
	v_pk_mul_f32 v[148:149], v[118:119], v[148:149]
	v_exp_f32_e32 v146, v146
	v_exp_f32_e32 v148, v148
	v_exp_f32_e32 v147, v147
	v_exp_f32_e32 v149, v149
	v_pk_add_f32 v[146:147], v[146:147], 1.0 op_sel_hi:[1,0]
	v_pk_add_f32 v[148:149], v[148:149], 1.0 op_sel_hi:[1,0]
	v_rcp_f32_e32 v146, v146
	v_rcp_f32_e32 v148, v148
	v_rcp_f32_e32 v147, v147
	v_rcp_f32_e32 v149, v149
	v_pk_mul_f32 v[120:121], v[120:121], v[146:147]
	v_pk_mul_f32 v[118:119], v[118:119], v[148:149]
.LBB0_1449:
	s_and_b64 vcc, exec, s[0:1]
	v_cvt_pk_bf16_f32 v152, v118, v119
	v_cvt_pk_bf16_f32 v153, v120, v121
	s_cbranch_vccnz .LBB0_1451
	v_pk_mul_f32 v[146:147], v[116:117], v[116:117]
	v_pk_mul_f32 v[148:149], v[114:115], v[114:115]
	v_mov_b64_e32 v[150:151], s[40:41]
	s_mov_b32 s2, 0xbdd2d3e8
	v_pk_fma_f32 v[146:147], v[146:147], s[2:3], v[150:151] op_sel_hi:[1,0,0]
	v_pk_fma_f32 v[148:149], v[148:149], s[2:3], v[150:151] op_sel_hi:[1,0,0]
	v_pk_mul_f32 v[146:147], v[116:117], v[146:147]
	v_pk_mul_f32 v[148:149], v[114:115], v[148:149]
	v_exp_f32_e32 v146, v146
	v_exp_f32_e32 v148, v148
	v_exp_f32_e32 v147, v147
	v_exp_f32_e32 v149, v149
	v_pk_add_f32 v[146:147], v[146:147], 1.0 op_sel_hi:[1,0]
	v_pk_add_f32 v[148:149], v[148:149], 1.0 op_sel_hi:[1,0]
	v_rcp_f32_e32 v146, v146
	v_rcp_f32_e32 v148, v148
	v_rcp_f32_e32 v147, v147
	v_rcp_f32_e32 v149, v149
	v_pk_mul_f32 v[116:117], v[116:117], v[146:147]
	v_pk_mul_f32 v[114:115], v[114:115], v[148:149]
.LBB0_1451:
	s_add_i32 s2, s38, -6
	s_cmp_lt_u32 s2, 4
	s_cselect_b64 s[8:9], -1, 0
	s_lshl_b32 s3, s38, 2
	s_add_i32 s94, s26, s3
	s_cmp_gt_u32 s2, 3
	s_mov_b32 s38, 0xbdd2d3e8
	v_cvt_pk_bf16_f32 v154, v114, v115
	v_cvt_pk_bf16_f32 v155, v116, v117
	s_nop 1
	v_permlane16_swap_b32_e32 v152, v154
	v_permlane16_swap_b32_e32 v153, v155
	v_lshl_add_u64 v[158:159], v[140:141], 0, v[156:157]
	global_store_dwordx4 v[158:159], v[152:155], off offset:256
	s_nop 1
	s_cbranch_scc1 .LBB0_1455
	v_mov_b32_e32 v140, v128
	v_mov_b32_e32 v141, v126
	v_mov_b32_e32 v146, v129
	v_mov_b32_e32 v147, v126
	v_pk_add_f32 v[148:149], v[140:141], v[146:147]
	v_pk_mul_f32 v[140:141], v[140:141], v[146:147]
	v_mul_f32_e32 v147, v124, v124
	v_mov_b32_e32 v149, v141
	v_pk_add_f32 v[140:141], v[126:127], v[126:127] op_sel:[1,0]
	v_pk_mul_f32 v[126:127], v[126:127], v[126:127]
	v_mov_b32_e32 v146, v124
	v_mov_b32_e32 v141, v127
	v_pk_add_f32 v[126:127], v[140:141], v[148:149]
	v_mul_f32_e32 v140, v128, v128
	v_pk_fma_f32 v[128:129], v[128:129], v[128:129], v[140:141] op_sel_hi:[1,1,0]
	v_mul_f32_e32 v141, v123, v123
	v_mov_b32_e32 v128, v65
	v_pk_add_f32 v[126:127], v[126:127], v[128:129]
	v_mul_f32_e32 v129, v122, v122
	v_mul_f32_e32 v149, v125, v125
	v_mov_b32_e32 v128, v122
	v_mov_b32_e32 v140, v123
	v_mov_b32_e32 v148, v125
	v_pk_add_f32 v[122:123], v[128:129], v[140:141]
	v_pk_add_f32 v[124:125], v[146:147], v[148:149]
	v_mul_f32_e32 v129, v120, v120
	v_pk_add_f32 v[122:123], v[122:123], v[124:125]
	v_mul_f32_e32 v125, v118, v118
	v_pk_add_f32 v[122:123], v[126:127], v[122:123]
	v_mul_f32_e32 v127, v119, v119
	v_mul_f32_e32 v141, v121, v121
	v_mov_b32_e32 v124, v118
	v_mov_b32_e32 v126, v119
	v_mov_b32_e32 v128, v120
	v_mov_b32_e32 v140, v121
	v_pk_add_f32 v[118:119], v[124:125], v[126:127]
	v_pk_add_f32 v[120:121], v[128:129], v[140:141]
	v_cmp_lt_i32_e32 vcc, v206, v204
	v_pk_add_f32 v[118:119], v[118:119], v[120:121]
	v_mul_f32_e32 v121, v114, v114
	v_cndmask_b32_e32 v120, v203, v206, vcc
	v_pk_add_f32 v[118:119], v[122:123], v[118:119]
	v_mul_f32_e32 v123, v115, v115
	v_mul_f32_e32 v125, v116, v116
	v_mul_f32_e32 v127, v117, v117
	v_lshlrev_b32_e32 v128, 2, v120
	v_mov_b32_e32 v120, v114
	v_mov_b32_e32 v122, v115
	v_mov_b32_e32 v124, v116
	v_mov_b32_e32 v126, v117
	v_pk_add_f32 v[114:115], v[120:121], v[122:123]
	v_pk_add_f32 v[116:117], v[124:125], v[126:127]
	v_cmp_lt_i32_e32 vcc, v205, v204
	v_pk_add_f32 v[114:115], v[114:115], v[116:117]
	s_nop 0
	v_pk_add_f32 v[114:115], v[118:119], v[114:115]
	ds_bpermute_b32 v116, v128, v114
	ds_bpermute_b32 v117, v128, v115
	v_cndmask_b32_e32 v118, v203, v205, vcc
	v_lshlrev_b32_e32 v118, 2, v118
	s_waitcnt lgkmcnt(0)
	v_pk_add_f32 v[114:115], v[114:115], v[116:117]
	ds_bpermute_b32 v116, v118, v114
	ds_bpermute_b32 v117, v118, v115
	s_and_saveexec_b64 s[2:3], s[6:7]
	s_cbranch_execz .LBB0_1454
	v_readlane_b32 s4, v249, 5
	v_lshlrev_b64 v[118:119], 7, v[138:139]
	v_readlane_b32 s5, v249, 6
	s_waitcnt lgkmcnt(0)
	v_pk_add_f32 v[114:115], v[114:115], v[116:117]
	v_lshl_add_u64 v[118:119], s[4:5], 0, v[118:119]
	v_lshl_add_u64 v[118:119], s[94:95], 3, v[118:119]
	global_store_dwordx2 v[118:119], v[114:115], off

; __device__ __forceinline__ unsigned cvt_pk_bf16(float lo, float hi) { unsigned r; asm volatile("v_cvt_pk_bf16_f32 %0, %1, %2" : "=v"(r) : "v"(lo), "v"(hi)); return r; }
; __device__ __forceinline__ f32x4 gelu4(const f32x4 x) {
;     const f32x4 t = x * x, a = x * (t * -0.10294324f + -2.3022082f);
;     f32x4 e; e[0] = __builtin_amdgcn_exp2f(a[0]); e[1] = __builtin_amdgcn_exp2f(a[1]); e[2] = __builtin_amdgcn_exp2f(a[2]); e[3] = __builtin_amdgcn_exp2f(a[3]);
;     const f32x4 d = e + 1.0f;
;     f32x4 r; r[0] = __builtin_amdgcn_rcpf(d[0]); r[1] = __builtin_amdgcn_rcpf(d[1]); r[2] = __builtin_amdgcn_rcpf(d[2]); r[3] = __builtin_amdgcn_rcpf(d[3]);
;     return x * r;
; }
;     __device__ __forceinline__ void operator()(const f32x4 (&acc)[2][2][4][2], const Unit& u, int wr, int wc, int fr, int fq) const {
;     ...
;             for (int m = 0; m < 4; ++m) {
;                 const int row = row0 + ai * HALF + m * 16; bf16_t* rowp = proj + (size_t)row * INW + col0; float s = 0.f, q = 0.f;
; #pragma unroll
;                 for (int bj = 0; bj < 2; ++bj)
; #pragma unroll
;                     for (int n = 0; n < 2; ++n) { f32x4 v = acc[ai][bj][m][n];
;                         if (act) v = gelu4(v);
;                         s += (v[0] + v[1]) + (v[2] + v[3]); q += (v[0] * v[0] + v[1] * v[1]) + (v[2] * v[2] + v[3] * v[3]);
;                         u32x2 pk; pk.x = cvt_pk_bf16(v[0], v[1]); pk.y = cvt_pk_bf16(v[2], v[3]); *(u32x2*)(rowp + bj * HALF + n * 16) = pk; }
;                 if (st) { s += __shfl_xor(s, 16); s += __shfl_xor(s, 32); q += __shfl_xor(q, 16); q += __shfl_xor(q, 32);
;                     if (fq == 0) { float* sp = stats + ((size_t)row * 16 + (u.pn - 6) * 4 + wc) * 2; sp[0] = s; sp[1] = q; } }
.LBB0_1457:
	v_or_b32_e32 v114, 16, v138
	v_ashrrev_i32_e32 v115, 31, v114
	s_waitcnt lgkmcnt(0)
	v_lshlrev_b64 v[116:117], 13, v[114:115]
	v_lshl_add_u64 v[116:117], s[80:81], 0, v[116:117]
	v_lshl_add_u64 v[116:117], v[136:137], 1, v[116:117]
	s_and_b64 vcc, exec, s[0:1]
	v_cvt_pk_bf16_f32 v152, v110, v111
	v_cvt_pk_bf16_f32 v153, v112, v113
	s_cbranch_vccnz .LBB0_1459
	v_pk_mul_f32 v[118:119], v[108:109], v[108:109]
	v_pk_mul_f32 v[120:121], v[106:107], v[106:107]
	v_mov_b64_e32 v[122:123], s[40:41]
	v_pk_fma_f32 v[118:119], v[118:119], s[38:39], v[122:123] op_sel_hi:[1,0,0]
	v_pk_fma_f32 v[120:121], v[120:121], s[38:39], v[122:123] op_sel_hi:[1,0,0]
	v_pk_mul_f32 v[118:119], v[108:109], v[118:119]
	v_pk_mul_f32 v[120:121], v[106:107], v[120:121]
	v_exp_f32_e32 v118, v118
	v_exp_f32_e32 v120, v120
	v_exp_f32_e32 v119, v119
	v_exp_f32_e32 v121, v121
	v_pk_add_f32 v[118:119], v[118:119], 1.0 op_sel_hi:[1,0]
	v_pk_add_f32 v[120:121], v[120:121], 1.0 op_sel_hi:[1,0]
	v_rcp_f32_e32 v118, v118
	v_rcp_f32_e32 v120, v120
	v_rcp_f32_e32 v119, v119
	v_rcp_f32_e32 v121, v121
	v_pk_mul_f32 v[108:109], v[108:109], v[118:119]
	v_pk_mul_f32 v[106:107], v[106:107], v[120:121]
.LBB0_1459:
	s_and_b64 vcc, exec, s[0:1]
	v_cvt_pk_bf16_f32 v154, v106, v107
	v_cvt_pk_bf16_f32 v155, v108, v109
	s_nop 1
	v_permlane16_swap_b32_e32 v152, v154
	v_permlane16_swap_b32_e32 v153, v155
	v_lshl_add_u64 v[158:159], v[116:117], 0, v[156:157]
	global_store_dwordx4 v[158:159], v[152:155], off
	s_nop 1
	s_cbranch_vccnz .LBB0_1461
	v_pk_mul_f32 v[118:119], v[104:105], v[104:105]
	v_pk_mul_f32 v[120:121], v[102:103], v[102:103]
	v_mov_b64_e32 v[122:123], s[40:41]
	v_pk_fma_f32 v[118:119], v[118:119], s[38:39], v[122:123] op_sel_hi:[1,0,0]
	v_pk_fma_f32 v[120:121], v[120:121], s[38:39], v[122:123] op_sel_hi:[1,0,0]
	v_pk_mul_f32 v[118:119], v[104:105], v[118:119]
	v_pk_mul_f32 v[120:121], v[102:103], v[120:121]
	v_exp_f32_e32 v118, v118
	v_exp_f32_e32 v120, v120
	v_exp_f32_e32 v119, v119
	v_exp_f32_e32 v121, v121
	v_pk_add_f32 v[118:119], v[118:119], 1.0 op_sel_hi:[1,0]
	v_pk_add_f32 v[120:121], v[120:121], 1.0 op_sel_hi:[1,0]
	v_rcp_f32_e32 v118, v118
	v_rcp_f32_e32 v120, v120
	v_rcp_f32_e32 v119, v119
	v_rcp_f32_e32 v121, v121
	v_pk_mul_f32 v[104:105], v[104:105], v[118:119]
	v_pk_mul_f32 v[102:103], v[102:103], v[120:121]
.LBB0_1461:
	s_and_b64 vcc, exec, s[0:1]
	v_cvt_pk_bf16_f32 v152, v102, v103
	v_cvt_pk_bf16_f32 v153, v104, v105
	s_cbranch_vccnz .LBB0_1463
	v_pk_mul_f32 v[118:119], v[100:101], v[100:101]
	v_pk_mul_f32 v[120:121], v[98:99], v[98:99]
	v_mov_b64_e32 v[122:123], s[40:41]
	v_pk_fma_f32 v[118:119], v[118:119], s[38:39], v[122:123] op_sel_hi:[1,0,0]
	v_pk_fma_f32 v[120:121], v[120:121], s[38:39], v[122:123] op_sel_hi:[1,0,0]
	v_pk_mul_f32 v[118:119], v[100:101], v[118:119]
	v_pk_mul_f32 v[120:121], v[98:99], v[120:121]
	v_exp_f32_e32 v118, v118
	v_exp_f32_e32 v120, v120
	v_exp_f32_e32 v119, v119
	v_exp_f32_e32 v121, v121
	v_pk_add_f32 v[118:119], v[118:119], 1.0 op_sel_hi:[1,0]
	v_pk_add_f32 v[120:121], v[120:121], 1.0 op_sel_hi:[1,0]
	v_rcp_f32_e32 v118, v118
	v_rcp_f32_e32 v120, v120
	v_rcp_f32_e32 v119, v119
	v_rcp_f32_e32 v121, v121
	v_pk_mul_f32 v[100:101], v[100:101], v[118:119]
	v_pk_mul_f32 v[98:99], v[98:99], v[120:121]

; __device__ __forceinline__ unsigned cvt_pk_bf16(float lo, float hi) { unsigned r; asm volatile("v_cvt_pk_bf16_f32 %0, %1, %2" : "=v"(r) : "v"(lo), "v"(hi)); return r; }
; __device__ __forceinline__ f32x4 gelu4(const f32x4 x) {
;     const f32x4 t = x * x, a = x * (t * -0.10294324f + -2.3022082f);
;     f32x4 e; e[0] = __builtin_amdgcn_exp2f(a[0]); e[1] = __builtin_amdgcn_exp2f(a[1]); e[2] = __builtin_amdgcn_exp2f(a[2]); e[3] = __builtin_amdgcn_exp2f(a[3]);
;     const f32x4 d = e + 1.0f;
;     f32x4 r; r[0] = __builtin_amdgcn_rcpf(d[0]); r[1] = __builtin_amdgcn_rcpf(d[1]); r[2] = __builtin_amdgcn_rcpf(d[2]); r[3] = __builtin_amdgcn_rcpf(d[3]);
;     return x * r;
; }
;     __device__ __forceinline__ void operator()(const f32x4 (&acc)[2][2][4][2], const Unit& u, int wr, int wc, int fr, int fq) const {
;     ...
;             for (int m = 0; m < 4; ++m) {
;                 const int row = row0 + ai * HALF + m * 16; bf16_t* rowp = proj + (size_t)row * INW + col0; float s = 0.f, q = 0.f;
; #pragma unroll
;                 for (int bj = 0; bj < 2; ++bj)
; #pragma unroll
;                     for (int n = 0; n < 2; ++n) { f32x4 v = acc[ai][bj][m][n];
;                         if (act) v = gelu4(v);
;                         s += (v[0] + v[1]) + (v[2] + v[3]); q += (v[0] * v[0] + v[1] * v[1]) + (v[2] * v[2] + v[3] * v[3]);
;                         u32x2 pk; pk.x = cvt_pk_bf16(v[0], v[1]); pk.y = cvt_pk_bf16(v[2], v[3]); *(u32x2*)(rowp + bj * HALF + n * 16) = pk; }
;                 if (st) { s += __shfl_xor(s, 16); s += __shfl_xor(s, 32); q += __shfl_xor(q, 16); q += __shfl_xor(q, 32);
;                     if (fq == 0) { float* sp = stats + ((size_t)row * 16 + (u.pn - 6) * 4 + wc) * 2; sp[0] = s; sp[1] = q; } }
.LBB0_1469:
	v_or_b32_e32 v98, 32, v138
	v_ashrrev_i32_e32 v99, 31, v98
	s_waitcnt lgkmcnt(0)
	v_lshlrev_b64 v[100:101], 13, v[98:99]
	v_lshl_add_u64 v[100:101], s[80:81], 0, v[100:101]
	v_lshl_add_u64 v[100:101], v[136:137], 1, v[100:101]
	s_and_b64 vcc, exec, s[0:1]
	v_cvt_pk_bf16_f32 v152, v94, v95
	v_cvt_pk_bf16_f32 v153, v96, v97
	s_cbranch_vccnz .LBB0_1471
	v_pk_mul_f32 v[102:103], v[92:93], v[92:93]
	v_pk_mul_f32 v[104:105], v[90:91], v[90:91]
	v_mov_b64_e32 v[106:107], s[40:41]
	v_pk_fma_f32 v[102:103], v[102:103], s[38:39], v[106:107] op_sel_hi:[1,0,0]
	v_pk_fma_f32 v[104:105], v[104:105], s[38:39], v[106:107] op_sel_hi:[1,0,0]
	v_pk_mul_f32 v[102:103], v[92:93], v[102:103]
	v_pk_mul_f32 v[104:105], v[90:91], v[104:105]
	v_exp_f32_e32 v102, v102
	v_exp_f32_e32 v104, v104
	v_exp_f32_e32 v103, v103
	v_exp_f32_e32 v105, v105
	v_pk_add_f32 v[102:103], v[102:103], 1.0 op_sel_hi:[1,0]
	v_pk_add_f32 v[104:105], v[104:105], 1.0 op_sel_hi:[1,0]
	v_rcp_f32_e32 v102, v102
	v_rcp_f32_e32 v104, v104
	v_rcp_f32_e32 v103, v103
	v_rcp_f32_e32 v105, v105
	v_pk_mul_f32 v[92:93], v[92:93], v[102:103]
	v_pk_mul_f32 v[90:91], v[90:91], v[104:105]
.LBB0_1471:
	s_and_b64 vcc, exec, s[0:1]
	v_cvt_pk_bf16_f32 v154, v90, v91
	v_cvt_pk_bf16_f32 v155, v92, v93
	s_nop 1
	v_permlane16_swap_b32_e32 v152, v154
	v_permlane16_swap_b32_e32 v153, v155
	v_lshl_add_u64 v[158:159], v[100:101], 0, v[156:157]
	global_store_dwordx4 v[158:159], v[152:155], off
	s_nop 1
	s_cbranch_vccnz .LBB0_1473
	v_pk_mul_f32 v[102:103], v[88:89], v[88:89]
	v_pk_mul_f32 v[104:105], v[86:87], v[86:87]
	v_mov_b64_e32 v[106:107], s[40:41]
	v_pk_fma_f32 v[102:103], v[102:103], s[38:39], v[106:107] op_sel_hi:[1,0,0]
	v_pk_fma_f32 v[104:105], v[104:105], s[38:39], v[106:107] op_sel_hi:[1,0,0]
	v_pk_mul_f32 v[102:103], v[88:89], v[102:103]
	v_pk_mul_f32 v[104:105], v[86:87], v[104:105]
	v_exp_f32_e32 v102, v102
	v_exp_f32_e32 v104, v104
	v_exp_f32_e32 v103, v103
	v_exp_f32_e32 v105, v105
	v_pk_add_f32 v[102:103], v[102:103], 1.0 op_sel_hi:[1,0]
	v_pk_add_f32 v[104:105], v[104:105], 1.0 op_sel_hi:[1,0]
	v_rcp_f32_e32 v102, v102
	v_rcp_f32_e32 v104, v104
	v_rcp_f32_e32 v103, v103
	v_rcp_f32_e32 v105, v105
	v_pk_mul_f32 v[88:89], v[88:89], v[102:103]
	v_pk_mul_f32 v[86:87], v[86:87], v[104:105]
.LBB0_1473:
	s_and_b64 vcc, exec, s[0:1]
	v_cvt_pk_bf16_f32 v152, v86, v87
	v_cvt_pk_bf16_f32 v153, v88, v89
	s_cbranch_vccnz .LBB0_1475
	v_pk_mul_f32 v[102:103], v[84:85], v[84:85]
	v_pk_mul_f32 v[104:105], v[82:83], v[82:83]
	v_mov_b64_e32 v[106:107], s[40:41]
	v_pk_fma_f32 v[102:103], v[102:103], s[38:39], v[106:107] op_sel_hi:[1,0,0]
	v_pk_fma_f32 v[104:105], v[104:105], s[38:39], v[106:107] op_sel_hi:[1,0,0]
	v_pk_mul_f32 v[102:103], v[84:85], v[102:103]
	v_pk_mul_f32 v[104:105], v[82:83], v[104:105]
	v_exp_f32_e32 v102, v102
	v_exp_f32_e32 v104, v104
	v_exp_f32_e32 v103, v103
	v_exp_f32_e32 v105, v105
	v_pk_add_f32 v[102:103], v[102:103], 1.0 op_sel_hi:[1,0]
	v_pk_add_f32 v[104:105], v[104:105], 1.0 op_sel_hi:[1,0]
	v_rcp_f32_e32 v102, v102
	v_rcp_f32_e32 v104, v104
	v_rcp_f32_e32 v103, v103
	v_rcp_f32_e32 v105, v105
	v_pk_mul_f32 v[84:85], v[84:85], v[102:103]
	v_pk_mul_f32 v[82:83], v[82:83], v[104:105]

; __device__ __forceinline__ unsigned cvt_pk_bf16(float lo, float hi) { unsigned r; asm volatile("v_cvt_pk_bf16_f32 %0, %1, %2" : "=v"(r) : "v"(lo), "v"(hi)); return r; }
; __device__ __forceinline__ f32x4 gelu4(const f32x4 x) {
;     const f32x4 t = x * x, a = x * (t * -0.10294324f + -2.3022082f);
;     f32x4 e; e[0] = __builtin_amdgcn_exp2f(a[0]); e[1] = __builtin_amdgcn_exp2f(a[1]); e[2] = __builtin_amdgcn_exp2f(a[2]); e[3] = __builtin_amdgcn_exp2f(a[3]);
;     const f32x4 d = e + 1.0f;
;     f32x4 r; r[0] = __builtin_amdgcn_rcpf(d[0]); r[1] = __builtin_amdgcn_rcpf(d[1]); r[2] = __builtin_amdgcn_rcpf(d[2]); r[3] = __builtin_amdgcn_rcpf(d[3]);
;     return x * r;
; }
;     __device__ __forceinline__ void operator()(const f32x4 (&acc)[2][2][4][2], const Unit& u, int wr, int wc, int fr, int fq) const {
;     ...
;             for (int m = 0; m < 4; ++m) {
;                 const int row = row0 + ai * HALF + m * 16; bf16_t* rowp = proj + (size_t)row * INW + col0; float s = 0.f, q = 0.f;
; #pragma unroll
;                 for (int bj = 0; bj < 2; ++bj)
; #pragma unroll
;                     for (int n = 0; n < 2; ++n) { f32x4 v = acc[ai][bj][m][n];
;                         if (act) v = gelu4(v);
;                         s += (v[0] + v[1]) + (v[2] + v[3]); q += (v[0] * v[0] + v[1] * v[1]) + (v[2] * v[2] + v[3] * v[3]);
;                         u32x2 pk; pk.x = cvt_pk_bf16(v[0], v[1]); pk.y = cvt_pk_bf16(v[2], v[3]); *(u32x2*)(rowp + bj * HALF + n * 16) = pk; }
;                 if (st) { s += __shfl_xor(s, 16); s += __shfl_xor(s, 32); q += __shfl_xor(q, 16); q += __shfl_xor(q, 32);
;                     if (fq == 0) { float* sp = stats + ((size_t)row * 16 + (u.pn - 6) * 4 + wc) * 2; sp[0] = s; sp[1] = q; } }
.LBB0_1481:
	v_or_b32_e32 v82, 48, v138
	v_ashrrev_i32_e32 v83, 31, v82
	s_waitcnt lgkmcnt(0)
	v_lshlrev_b64 v[84:85], 13, v[82:83]
	v_lshl_add_u64 v[84:85], s[80:81], 0, v[84:85]
	v_lshl_add_u64 v[84:85], v[136:137], 1, v[84:85]
	s_and_b64 vcc, exec, s[0:1]
	v_cvt_pk_bf16_f32 v152, v78, v79
	v_cvt_pk_bf16_f32 v153, v80, v81
	s_cbranch_vccnz .LBB0_1483
	v_pk_mul_f32 v[86:87], v[76:77], v[76:77]
	v_pk_mul_f32 v[88:89], v[74:75], v[74:75]
	v_mov_b64_e32 v[90:91], s[40:41]
	v_pk_fma_f32 v[86:87], v[86:87], s[38:39], v[90:91] op_sel_hi:[1,0,0]
	v_pk_fma_f32 v[88:89], v[88:89], s[38:39], v[90:91] op_sel_hi:[1,0,0]
	v_pk_mul_f32 v[86:87], v[76:77], v[86:87]
	v_pk_mul_f32 v[88:89], v[74:75], v[88:89]
	v_exp_f32_e32 v86, v86
	v_exp_f32_e32 v88, v88
	v_exp_f32_e32 v87, v87
	v_exp_f32_e32 v89, v89
	v_pk_add_f32 v[86:87], v[86:87], 1.0 op_sel_hi:[1,0]
	v_pk_add_f32 v[88:89], v[88:89], 1.0 op_sel_hi:[1,0]
	v_rcp_f32_e32 v86, v86
	v_rcp_f32_e32 v88, v88
	v_rcp_f32_e32 v87, v87
	v_rcp_f32_e32 v89, v89
	v_pk_mul_f32 v[76:77], v[76:77], v[86:87]
	v_pk_mul_f32 v[74:75], v[74:75], v[88:89]
.LBB0_1483:
	s_and_b64 vcc, exec, s[0:1]
	v_cvt_pk_bf16_f32 v154, v74, v75
	v_cvt_pk_bf16_f32 v155, v76, v77
	s_nop 1
	v_permlane16_swap_b32_e32 v152, v154
	v_permlane16_swap_b32_e32 v153, v155
	v_lshl_add_u64 v[158:159], v[84:85], 0, v[156:157]
	global_store_dwordx4 v[158:159], v[152:155], off
	s_nop 1
	s_cbranch_vccnz .LBB0_1485
	v_pk_mul_f32 v[86:87], v[72:73], v[72:73]
	v_pk_mul_f32 v[88:89], v[70:71], v[70:71]
	v_mov_b64_e32 v[90:91], s[40:41]
	v_pk_fma_f32 v[86:87], v[86:87], s[38:39], v[90:91] op_sel_hi:[1,0,0]
	v_pk_fma_f32 v[88:89], v[88:89], s[38:39], v[90:91] op_sel_hi:[1,0,0]
	v_pk_mul_f32 v[86:87], v[72:73], v[86:87]
	v_pk_mul_f32 v[88:89], v[70:71], v[88:89]
	v_exp_f32_e32 v86, v86
	v_exp_f32_e32 v88, v88
	v_exp_f32_e32 v87, v87
	v_exp_f32_e32 v89, v89
	v_pk_add_f32 v[86:87], v[86:87], 1.0 op_sel_hi:[1,0]
	v_pk_add_f32 v[88:89], v[88:89], 1.0 op_sel_hi:[1,0]
	v_rcp_f32_e32 v86, v86
	v_rcp_f32_e32 v88, v88
	v_rcp_f32_e32 v87, v87
	v_rcp_f32_e32 v89, v89
	v_pk_mul_f32 v[72:73], v[72:73], v[86:87]
	v_pk_mul_f32 v[70:71], v[70:71], v[88:89]
.LBB0_1485:
	s_and_b64 vcc, exec, s[0:1]
	v_cvt_pk_bf16_f32 v152, v70, v71
	v_cvt_pk_bf16_f32 v153, v72, v73
	s_cbranch_vccnz .LBB0_1487
	v_pk_mul_f32 v[86:87], v[68:69], v[68:69]
	v_pk_mul_f32 v[88:89], v[66:67], v[66:67]
	v_mov_b64_e32 v[90:91], s[40:41]
	v_pk_fma_f32 v[86:87], v[86:87], s[38:39], v[90:91] op_sel_hi:[1,0,0]
	v_pk_fma_f32 v[88:89], v[88:89], s[38:39], v[90:91] op_sel_hi:[1,0,0]
	v_pk_mul_f32 v[86:87], v[68:69], v[86:87]
	v_pk_mul_f32 v[88:89], v[66:67], v[88:89]
	v_exp_f32_e32 v86, v86
	v_exp_f32_e32 v88, v88
	v_exp_f32_e32 v87, v87
	v_exp_f32_e32 v89, v89
	v_pk_add_f32 v[86:87], v[86:87], 1.0 op_sel_hi:[1,0]
	v_pk_add_f32 v[88:89], v[88:89], 1.0 op_sel_hi:[1,0]
	v_rcp_f32_e32 v86, v86
	v_rcp_f32_e32 v88, v88
	v_rcp_f32_e32 v87, v87
	v_rcp_f32_e32 v89, v89
	v_pk_mul_f32 v[68:69], v[68:69], v[86:87]
	v_pk_mul_f32 v[66:67], v[66:67], v[88:89]

; __device__ __forceinline__ unsigned cvt_pk_bf16(float lo, float hi) { unsigned r; asm volatile("v_cvt_pk_bf16_f32 %0, %1, %2" : "=v"(r) : "v"(lo), "v"(hi)); return r; }
; __device__ __forceinline__ f32x4 gelu4(const f32x4 x) {
;     const f32x4 t = x * x, a = x * (t * -0.10294324f + -2.3022082f);
;     f32x4 e; e[0] = __builtin_amdgcn_exp2f(a[0]); e[1] = __builtin_amdgcn_exp2f(a[1]); e[2] = __builtin_amdgcn_exp2f(a[2]); e[3] = __builtin_amdgcn_exp2f(a[3]);
;     const f32x4 d = e + 1.0f;
;     f32x4 r; r[0] = __builtin_amdgcn_rcpf(d[0]); r[1] = __builtin_amdgcn_rcpf(d[1]); r[2] = __builtin_amdgcn_rcpf(d[2]); r[3] = __builtin_amdgcn_rcpf(d[3]);
;     return x * r;
; }
;     __device__ __forceinline__ void operator()(const f32x4 (&acc)[2][2][4][2], const Unit& u, int wr, int wc, int fr, int fq) const {
;     ...
;             for (int m = 0; m < 4; ++m) {
;                 const int row = row0 + ai * HALF + m * 16; bf16_t* rowp = proj + (size_t)row * INW + col0; float s = 0.f, q = 0.f;
; #pragma unroll
;                 for (int bj = 0; bj < 2; ++bj)
; #pragma unroll
;                     for (int n = 0; n < 2; ++n) { f32x4 v = acc[ai][bj][m][n];
;                         if (act) v = gelu4(v);
;                         s += (v[0] + v[1]) + (v[2] + v[3]); q += (v[0] * v[0] + v[1] * v[1]) + (v[2] * v[2] + v[3] * v[3]);
;                         u32x2 pk; pk.x = cvt_pk_bf16(v[0], v[1]); pk.y = cvt_pk_bf16(v[2], v[3]); *(u32x2*)(rowp + bj * HALF + n * 16) = pk; }
;                 if (st) { s += __shfl_xor(s, 16); s += __shfl_xor(s, 32); q += __shfl_xor(q, 16); q += __shfl_xor(q, 32);
;                     if (fq == 0) { float* sp = stats + ((size_t)row * 16 + (u.pn - 6) * 4 + wc) * 2; sp[0] = s; sp[1] = q; } }
.LBB0_1493:
	v_add_u32_e32 v66, 0x80, v138
	v_ashrrev_i32_e32 v67, 31, v66
	s_waitcnt lgkmcnt(0)
	v_lshlrev_b64 v[68:69], 13, v[66:67]
	v_lshl_add_u64 v[68:69], s[80:81], 0, v[68:69]
	v_lshl_add_u64 v[68:69], v[136:137], 1, v[68:69]
	s_and_b64 vcc, exec, s[0:1]
	v_cvt_pk_bf16_f32 v152, v60, v61
	v_cvt_pk_bf16_f32 v153, v62, v63
	s_cbranch_vccnz .LBB0_1495
	v_pk_mul_f32 v[70:71], v[58:59], v[58:59]
	v_pk_mul_f32 v[72:73], v[56:57], v[56:57]
	v_mov_b64_e32 v[74:75], s[40:41]
	v_pk_fma_f32 v[70:71], v[70:71], s[38:39], v[74:75] op_sel_hi:[1,0,0]
	v_pk_fma_f32 v[72:73], v[72:73], s[38:39], v[74:75] op_sel_hi:[1,0,0]
	v_pk_mul_f32 v[70:71], v[58:59], v[70:71]
	v_pk_mul_f32 v[72:73], v[56:57], v[72:73]
	v_exp_f32_e32 v70, v70
	v_exp_f32_e32 v72, v72
	v_exp_f32_e32 v71, v71
	v_exp_f32_e32 v73, v73
	v_pk_add_f32 v[70:71], v[70:71], 1.0 op_sel_hi:[1,0]
	v_pk_add_f32 v[72:73], v[72:73], 1.0 op_sel_hi:[1,0]
	v_rcp_f32_e32 v70, v70
	v_rcp_f32_e32 v72, v72
	v_rcp_f32_e32 v71, v71
	v_rcp_f32_e32 v73, v73
	v_pk_mul_f32 v[58:59], v[58:59], v[70:71]
	v_pk_mul_f32 v[56:57], v[56:57], v[72:73]
.LBB0_1495:
	s_and_b64 vcc, exec, s[0:1]
	v_cvt_pk_bf16_f32 v154, v56, v57
	v_cvt_pk_bf16_f32 v155, v58, v59
	s_nop 1
	v_permlane16_swap_b32_e32 v152, v154
	v_permlane16_swap_b32_e32 v153, v155
	v_lshl_add_u64 v[158:159], v[68:69], 0, v[156:157]
	global_store_dwordx4 v[158:159], v[152:155], off
	s_nop 1
	s_cbranch_vccnz .LBB0_1497
	v_pk_mul_f32 v[70:71], v[54:55], v[54:55]
	v_pk_mul_f32 v[72:73], v[52:53], v[52:53]
	v_mov_b64_e32 v[74:75], s[40:41]
	v_pk_fma_f32 v[70:71], v[70:71], s[38:39], v[74:75] op_sel_hi:[1,0,0]
	v_pk_fma_f32 v[72:73], v[72:73], s[38:39], v[74:75] op_sel_hi:[1,0,0]
	v_pk_mul_f32 v[70:71], v[54:55], v[70:71]
	v_pk_mul_f32 v[72:73], v[52:53], v[72:73]
	v_exp_f32_e32 v70, v70
	v_exp_f32_e32 v72, v72
	v_exp_f32_e32 v71, v71
	v_exp_f32_e32 v73, v73
	v_pk_add_f32 v[70:71], v[70:71], 1.0 op_sel_hi:[1,0]
	v_pk_add_f32 v[72:73], v[72:73], 1.0 op_sel_hi:[1,0]
	v_rcp_f32_e32 v70, v70
	v_rcp_f32_e32 v72, v72
	v_rcp_f32_e32 v71, v71
	v_rcp_f32_e32 v73, v73
	v_pk_mul_f32 v[54:55], v[54:55], v[70:71]
	v_pk_mul_f32 v[52:53], v[52:53], v[72:73]
.LBB0_1497:
	s_and_b64 vcc, exec, s[0:1]
	v_cvt_pk_bf16_f32 v152, v52, v53
	v_cvt_pk_bf16_f32 v153, v54, v55
	s_cbranch_vccnz .LBB0_1499
	v_pk_mul_f32 v[70:71], v[50:51], v[50:51]
	v_pk_mul_f32 v[72:73], v[48:49], v[48:49]
	v_mov_b64_e32 v[74:75], s[40:41]
	v_pk_fma_f32 v[70:71], v[70:71], s[38:39], v[74:75] op_sel_hi:[1,0,0]
	v_pk_fma_f32 v[72:73], v[72:73], s[38:39], v[74:75] op_sel_hi:[1,0,0]
	v_pk_mul_f32 v[70:71], v[50:51], v[70:71]
	v_pk_mul_f32 v[72:73], v[48:49], v[72:73]
	v_exp_f32_e32 v70, v70
	v_exp_f32_e32 v72, v72
	v_exp_f32_e32 v71, v71
	v_exp_f32_e32 v73, v73
	v_pk_add_f32 v[70:71], v[70:71], 1.0 op_sel_hi:[1,0]
	v_pk_add_f32 v[72:73], v[72:73], 1.0 op_sel_hi:[1,0]
	v_rcp_f32_e32 v70, v70
	v_rcp_f32_e32 v72, v72
	v_rcp_f32_e32 v71, v71
	v_rcp_f32_e32 v73, v73
	v_pk_mul_f32 v[50:51], v[50:51], v[70:71]
	v_pk_mul_f32 v[48:49], v[48:49], v[72:73]

; __device__ __forceinline__ unsigned cvt_pk_bf16(float lo, float hi) { unsigned r; asm volatile("v_cvt_pk_bf16_f32 %0, %1, %2" : "=v"(r) : "v"(lo), "v"(hi)); return r; }
; __device__ __forceinline__ f32x4 gelu4(const f32x4 x) {
;     const f32x4 t = x * x, a = x * (t * -0.10294324f + -2.3022082f);
;     f32x4 e; e[0] = __builtin_amdgcn_exp2f(a[0]); e[1] = __builtin_amdgcn_exp2f(a[1]); e[2] = __builtin_amdgcn_exp2f(a[2]); e[3] = __builtin_amdgcn_exp2f(a[3]);
;     const f32x4 d = e + 1.0f;
;     f32x4 r; r[0] = __builtin_amdgcn_rcpf(d[0]); r[1] = __builtin_amdgcn_rcpf(d[1]); r[2] = __builtin_amdgcn_rcpf(d[2]); r[3] = __builtin_amdgcn_rcpf(d[3]);
;     return x * r;
; }
;     __device__ __forceinline__ void operator()(const f32x4 (&acc)[2][2][4][2], const Unit& u, int wr, int wc, int fr, int fq) const {
;     ...
;             for (int m = 0; m < 4; ++m) {
;                 const int row = row0 + ai * HALF + m * 16; bf16_t* rowp = proj + (size_t)row * INW + col0; float s = 0.f, q = 0.f;
; #pragma unroll
;                 for (int bj = 0; bj < 2; ++bj)
; #pragma unroll
;                     for (int n = 0; n < 2; ++n) { f32x4 v = acc[ai][bj][m][n];
;                         if (act) v = gelu4(v);
;                         s += (v[0] + v[1]) + (v[2] + v[3]); q += (v[0] * v[0] + v[1] * v[1]) + (v[2] * v[2] + v[3] * v[3]);
;                         u32x2 pk; pk.x = cvt_pk_bf16(v[0], v[1]); pk.y = cvt_pk_bf16(v[2], v[3]); *(u32x2*)(rowp + bj * HALF + n * 16) = pk; }
;                 if (st) { s += __shfl_xor(s, 16); s += __shfl_xor(s, 32); q += __shfl_xor(q, 16); q += __shfl_xor(q, 32);
;                     if (fq == 0) { float* sp = stats + ((size_t)row * 16 + (u.pn - 6) * 4 + wc) * 2; sp[0] = s; sp[1] = q; } }
.LBB0_1505:
	v_add_u32_e32 v48, 0x90, v138
	v_ashrrev_i32_e32 v49, 31, v48
	s_waitcnt lgkmcnt(0)
	v_lshlrev_b64 v[50:51], 13, v[48:49]
	v_lshl_add_u64 v[50:51], s[80:81], 0, v[50:51]
	v_lshl_add_u64 v[50:51], v[136:137], 1, v[50:51]
	s_and_b64 vcc, exec, s[0:1]
	v_cvt_pk_bf16_f32 v152, v44, v45
	v_cvt_pk_bf16_f32 v153, v46, v47
	s_cbranch_vccnz .LBB0_1507
	v_pk_mul_f32 v[52:53], v[42:43], v[42:43]
	v_pk_mul_f32 v[54:55], v[40:41], v[40:41]
	v_mov_b64_e32 v[56:57], s[40:41]
	v_pk_fma_f32 v[52:53], v[52:53], s[38:39], v[56:57] op_sel_hi:[1,0,0]
	v_pk_fma_f32 v[54:55], v[54:55], s[38:39], v[56:57] op_sel_hi:[1,0,0]
	v_pk_mul_f32 v[52:53], v[42:43], v[52:53]
	v_pk_mul_f32 v[54:55], v[40:41], v[54:55]
	v_exp_f32_e32 v52, v52
	v_exp_f32_e32 v54, v54
	v_exp_f32_e32 v53, v53
	v_exp_f32_e32 v55, v55
	v_pk_add_f32 v[52:53], v[52:53], 1.0 op_sel_hi:[1,0]
	v_pk_add_f32 v[54:55], v[54:55], 1.0 op_sel_hi:[1,0]
	v_rcp_f32_e32 v52, v52
	v_rcp_f32_e32 v54, v54
	v_rcp_f32_e32 v53, v53
	v_rcp_f32_e32 v55, v55
	v_pk_mul_f32 v[42:43], v[42:43], v[52:53]
	v_pk_mul_f32 v[40:41], v[40:41], v[54:55]
.LBB0_1507:
	s_and_b64 vcc, exec, s[0:1]
	v_cvt_pk_bf16_f32 v154, v40, v41
	v_cvt_pk_bf16_f32 v155, v42, v43
	s_nop 1
	v_permlane16_swap_b32_e32 v152, v154
	v_permlane16_swap_b32_e32 v153, v155
	v_lshl_add_u64 v[158:159], v[50:51], 0, v[156:157]
	global_store_dwordx4 v[158:159], v[152:155], off
	s_nop 1
	s_cbranch_vccnz .LBB0_1509
	v_pk_mul_f32 v[52:53], v[38:39], v[38:39]
	v_pk_mul_f32 v[54:55], v[36:37], v[36:37]
	v_mov_b64_e32 v[56:57], s[40:41]
	v_pk_fma_f32 v[52:53], v[52:53], s[38:39], v[56:57] op_sel_hi:[1,0,0]
	v_pk_fma_f32 v[54:55], v[54:55], s[38:39], v[56:57] op_sel_hi:[1,0,0]
	v_pk_mul_f32 v[52:53], v[38:39], v[52:53]
	v_pk_mul_f32 v[54:55], v[36:37], v[54:55]
	v_exp_f32_e32 v52, v52
	v_exp_f32_e32 v54, v54
	v_exp_f32_e32 v53, v53
	v_exp_f32_e32 v55, v55
	v_pk_add_f32 v[52:53], v[52:53], 1.0 op_sel_hi:[1,0]
	v_pk_add_f32 v[54:55], v[54:55], 1.0 op_sel_hi:[1,0]
	v_rcp_f32_e32 v52, v52
	v_rcp_f32_e32 v54, v54
	v_rcp_f32_e32 v53, v53
	v_rcp_f32_e32 v55, v55
	v_pk_mul_f32 v[38:39], v[38:39], v[52:53]
	v_pk_mul_f32 v[36:37], v[36:37], v[54:55]
.LBB0_1509:
	s_and_b64 vcc, exec, s[0:1]
	v_cvt_pk_bf16_f32 v152, v36, v37
	v_cvt_pk_bf16_f32 v153, v38, v39
	s_cbranch_vccnz .LBB0_1511
	v_pk_mul_f32 v[52:53], v[34:35], v[34:35]
	v_pk_mul_f32 v[54:55], v[32:33], v[32:33]
	v_mov_b64_e32 v[56:57], s[40:41]
	v_pk_fma_f32 v[52:53], v[52:53], s[38:39], v[56:57] op_sel_hi:[1,0,0]
	v_pk_fma_f32 v[54:55], v[54:55], s[38:39], v[56:57] op_sel_hi:[1,0,0]
	v_pk_mul_f32 v[52:53], v[34:35], v[52:53]
	v_pk_mul_f32 v[54:55], v[32:33], v[54:55]
	v_exp_f32_e32 v52, v52
	v_exp_f32_e32 v54, v54
	v_exp_f32_e32 v53, v53
	v_exp_f32_e32 v55, v55
	v_pk_add_f32 v[52:53], v[52:53], 1.0 op_sel_hi:[1,0]
	v_pk_add_f32 v[54:55], v[54:55], 1.0 op_sel_hi:[1,0]
	v_rcp_f32_e32 v52, v52
	v_rcp_f32_e32 v54, v54
	v_rcp_f32_e32 v53, v53
	v_rcp_f32_e32 v55, v55
	v_pk_mul_f32 v[34:35], v[34:35], v[52:53]
	v_pk_mul_f32 v[32:33], v[32:33], v[54:55]

; __device__ __forceinline__ unsigned cvt_pk_bf16(float lo, float hi) { unsigned r; asm volatile("v_cvt_pk_bf16_f32 %0, %1, %2" : "=v"(r) : "v"(lo), "v"(hi)); return r; }
; __device__ __forceinline__ f32x4 gelu4(const f32x4 x) {
;     const f32x4 t = x * x, a = x * (t * -0.10294324f + -2.3022082f);
;     f32x4 e; e[0] = __builtin_amdgcn_exp2f(a[0]); e[1] = __builtin_amdgcn_exp2f(a[1]); e[2] = __builtin_amdgcn_exp2f(a[2]); e[3] = __builtin_amdgcn_exp2f(a[3]);
;     const f32x4 d = e + 1.0f;
;     f32x4 r; r[0] = __builtin_amdgcn_rcpf(d[0]); r[1] = __builtin_amdgcn_rcpf(d[1]); r[2] = __builtin_amdgcn_rcpf(d[2]); r[3] = __builtin_amdgcn_rcpf(d[3]);
;     return x * r;
; }
;     __device__ __forceinline__ void operator()(const f32x4 (&acc)[2][2][4][2], const Unit& u, int wr, int wc, int fr, int fq) const {
;     ...
;             for (int m = 0; m < 4; ++m) {
;                 const int row = row0 + ai * HALF + m * 16; bf16_t* rowp = proj + (size_t)row * INW + col0; float s = 0.f, q = 0.f;
; #pragma unroll
;                 for (int bj = 0; bj < 2; ++bj)
; #pragma unroll
;                     for (int n = 0; n < 2; ++n) { f32x4 v = acc[ai][bj][m][n];
;                         if (act) v = gelu4(v);
;                         s += (v[0] + v[1]) + (v[2] + v[3]); q += (v[0] * v[0] + v[1] * v[1]) + (v[2] * v[2] + v[3] * v[3]);
;                         u32x2 pk; pk.x = cvt_pk_bf16(v[0], v[1]); pk.y = cvt_pk_bf16(v[2], v[3]); *(u32x2*)(rowp + bj * HALF + n * 16) = pk; }
;                 if (st) { s += __shfl_xor(s, 16); s += __shfl_xor(s, 32); q += __shfl_xor(q, 16); q += __shfl_xor(q, 32);
;                     if (fq == 0) { float* sp = stats + ((size_t)row * 16 + (u.pn - 6) * 4 + wc) * 2; sp[0] = s; sp[1] = q; } }
.LBB0_1517:
	v_add_u32_e32 v32, 0xa0, v138
	v_ashrrev_i32_e32 v33, 31, v32
	s_waitcnt lgkmcnt(0)
	v_lshlrev_b64 v[34:35], 13, v[32:33]
	v_lshl_add_u64 v[34:35], s[80:81], 0, v[34:35]
	v_lshl_add_u64 v[34:35], v[136:137], 1, v[34:35]
	s_and_b64 vcc, exec, s[0:1]
	v_cvt_pk_bf16_f32 v152, v28, v29
	v_cvt_pk_bf16_f32 v153, v30, v31
	s_cbranch_vccnz .LBB0_1519
	v_pk_mul_f32 v[36:37], v[26:27], v[26:27]
	v_pk_mul_f32 v[38:39], v[24:25], v[24:25]
	v_mov_b64_e32 v[40:41], s[40:41]
	v_pk_fma_f32 v[36:37], v[36:37], s[38:39], v[40:41] op_sel_hi:[1,0,0]
	v_pk_fma_f32 v[38:39], v[38:39], s[38:39], v[40:41] op_sel_hi:[1,0,0]
	v_pk_mul_f32 v[36:37], v[26:27], v[36:37]
	v_pk_mul_f32 v[38:39], v[24:25], v[38:39]
	v_exp_f32_e32 v36, v36
	v_exp_f32_e32 v38, v38
	v_exp_f32_e32 v37, v37
	v_exp_f32_e32 v39, v39
	v_pk_add_f32 v[36:37], v[36:37], 1.0 op_sel_hi:[1,0]
	v_pk_add_f32 v[38:39], v[38:39], 1.0 op_sel_hi:[1,0]
	v_rcp_f32_e32 v36, v36
	v_rcp_f32_e32 v38, v38
	v_rcp_f32_e32 v37, v37
	v_rcp_f32_e32 v39, v39
	v_pk_mul_f32 v[26:27], v[26:27], v[36:37]
	v_pk_mul_f32 v[24:25], v[24:25], v[38:39]
.LBB0_1519:
	s_and_b64 vcc, exec, s[0:1]
	v_cvt_pk_bf16_f32 v154, v24, v25
	v_cvt_pk_bf16_f32 v155, v26, v27
	s_nop 1
	v_permlane16_swap_b32_e32 v152, v154
	v_permlane16_swap_b32_e32 v153, v155
	v_lshl_add_u64 v[158:159], v[34:35], 0, v[156:157]
	global_store_dwordx4 v[158:159], v[152:155], off
	s_nop 1
	s_cbranch_vccnz .LBB0_1521
	v_pk_mul_f32 v[36:37], v[22:23], v[22:23]
	v_pk_mul_f32 v[38:39], v[20:21], v[20:21]
	v_mov_b64_e32 v[40:41], s[40:41]
	v_pk_fma_f32 v[36:37], v[36:37], s[38:39], v[40:41] op_sel_hi:[1,0,0]
	v_pk_fma_f32 v[38:39], v[38:39], s[38:39], v[40:41] op_sel_hi:[1,0,0]
	v_pk_mul_f32 v[36:37], v[22:23], v[36:37]
	v_pk_mul_f32 v[38:39], v[20:21], v[38:39]
	v_exp_f32_e32 v36, v36
	v_exp_f32_e32 v38, v38
	v_exp_f32_e32 v37, v37
	v_exp_f32_e32 v39, v39
	v_pk_add_f32 v[36:37], v[36:37], 1.0 op_sel_hi:[1,0]
	v_pk_add_f32 v[38:39], v[38:39], 1.0 op_sel_hi:[1,0]
	v_rcp_f32_e32 v36, v36
	v_rcp_f32_e32 v38, v38
	v_rcp_f32_e32 v37, v37
	v_rcp_f32_e32 v39, v39
	v_pk_mul_f32 v[22:23], v[22:23], v[36:37]
	v_pk_mul_f32 v[20:21], v[20:21], v[38:39]
.LBB0_1521:
	s_and_b64 vcc, exec, s[0:1]
	v_cvt_pk_bf16_f32 v152, v20, v21
	v_cvt_pk_bf16_f32 v153, v22, v23
	s_cbranch_vccnz .LBB0_1523
	v_pk_mul_f32 v[36:37], v[18:19], v[18:19]
	v_pk_mul_f32 v[38:39], v[16:17], v[16:17]
	v_mov_b64_e32 v[40:41], s[40:41]
	v_pk_fma_f32 v[36:37], v[36:37], s[38:39], v[40:41] op_sel_hi:[1,0,0]
	v_pk_fma_f32 v[38:39], v[38:39], s[38:39], v[40:41] op_sel_hi:[1,0,0]
	v_pk_mul_f32 v[36:37], v[18:19], v[36:37]
	v_pk_mul_f32 v[38:39], v[16:17], v[38:39]
	v_exp_f32_e32 v36, v36
	v_exp_f32_e32 v38, v38
	v_exp_f32_e32 v37, v37
	v_exp_f32_e32 v39, v39
	v_pk_add_f32 v[36:37], v[36:37], 1.0 op_sel_hi:[1,0]
	v_pk_add_f32 v[38:39], v[38:39], 1.0 op_sel_hi:[1,0]
	v_rcp_f32_e32 v36, v36
	v_rcp_f32_e32 v38, v38
	v_rcp_f32_e32 v37, v37
	v_rcp_f32_e32 v39, v39
	v_pk_mul_f32 v[18:19], v[18:19], v[36:37]
	v_pk_mul_f32 v[16:17], v[16:17], v[38:39]

; __device__ __forceinline__ unsigned cvt_pk_bf16(float lo, float hi) { unsigned r; asm volatile("v_cvt_pk_bf16_f32 %0, %1, %2" : "=v"(r) : "v"(lo), "v"(hi)); return r; }
; __device__ __forceinline__ f32x4 gelu4(const f32x4 x) {
;     const f32x4 t = x * x, a = x * (t * -0.10294324f + -2.3022082f);
;     f32x4 e; e[0] = __builtin_amdgcn_exp2f(a[0]); e[1] = __builtin_amdgcn_exp2f(a[1]); e[2] = __builtin_amdgcn_exp2f(a[2]); e[3] = __builtin_amdgcn_exp2f(a[3]);
;     const f32x4 d = e + 1.0f;
;     f32x4 r; r[0] = __builtin_amdgcn_rcpf(d[0]); r[1] = __builtin_amdgcn_rcpf(d[1]); r[2] = __builtin_amdgcn_rcpf(d[2]); r[3] = __builtin_amdgcn_rcpf(d[3]);
;     return x * r;
; }
;     __device__ __forceinline__ void operator()(const f32x4 (&acc)[2][2][4][2], const Unit& u, int wr, int wc, int fr, int fq) const {
;     ...
;             for (int m = 0; m < 4; ++m) {
;                 const int row = row0 + ai * HALF + m * 16; bf16_t* rowp = proj + (size_t)row * INW + col0; float s = 0.f, q = 0.f;
; #pragma unroll
;                 for (int bj = 0; bj < 2; ++bj)
; #pragma unroll
;                     for (int n = 0; n < 2; ++n) { f32x4 v = acc[ai][bj][m][n];
;                         if (act) v = gelu4(v);
;                         s += (v[0] + v[1]) + (v[2] + v[3]); q += (v[0] * v[0] + v[1] * v[1]) + (v[2] * v[2] + v[3] * v[3]);
;                         u32x2 pk; pk.x = cvt_pk_bf16(v[0], v[1]); pk.y = cvt_pk_bf16(v[2], v[3]); *(u32x2*)(rowp + bj * HALF + n * 16) = pk; }
;                 if (st) { s += __shfl_xor(s, 16); s += __shfl_xor(s, 32); q += __shfl_xor(q, 16); q += __shfl_xor(q, 32);
;                     if (fq == 0) { float* sp = stats + ((size_t)row * 16 + (u.pn - 6) * 4 + wc) * 2; sp[0] = s; sp[1] = q; } }
.LBB0_1529:
	v_add_u32_e32 v16, 0xb0, v138
	v_ashrrev_i32_e32 v17, 31, v16
	s_waitcnt lgkmcnt(0)
	v_lshlrev_b64 v[18:19], 13, v[16:17]
	v_lshl_add_u64 v[18:19], s[80:81], 0, v[18:19]
	v_lshl_add_u64 v[18:19], v[136:137], 1, v[18:19]
	s_and_b64 vcc, exec, s[0:1]
	v_cvt_pk_bf16_f32 v152, v12, v13
	v_cvt_pk_bf16_f32 v153, v14, v15
	s_cbranch_vccnz .LBB0_1531
	v_pk_mul_f32 v[20:21], v[10:11], v[10:11]
	v_pk_mul_f32 v[22:23], v[8:9], v[8:9]
	v_mov_b64_e32 v[24:25], s[40:41]
	v_pk_fma_f32 v[20:21], v[20:21], s[38:39], v[24:25] op_sel_hi:[1,0,0]
	v_pk_fma_f32 v[22:23], v[22:23], s[38:39], v[24:25] op_sel_hi:[1,0,0]
	v_pk_mul_f32 v[20:21], v[10:11], v[20:21]
	v_pk_mul_f32 v[22:23], v[8:9], v[22:23]
	v_exp_f32_e32 v20, v20
	v_exp_f32_e32 v22, v22
	v_exp_f32_e32 v21, v21
	v_exp_f32_e32 v23, v23
	v_pk_add_f32 v[20:21], v[20:21], 1.0 op_sel_hi:[1,0]
	v_pk_add_f32 v[22:23], v[22:23], 1.0 op_sel_hi:[1,0]
	v_rcp_f32_e32 v20, v20
	v_rcp_f32_e32 v22, v22
	v_rcp_f32_e32 v21, v21
	v_rcp_f32_e32 v23, v23
	v_pk_mul_f32 v[10:11], v[10:11], v[20:21]
	v_pk_mul_f32 v[8:9], v[8:9], v[22:23]
.LBB0_1531:
	s_and_b64 vcc, exec, s[0:1]
	v_cvt_pk_bf16_f32 v154, v8, v9
	v_cvt_pk_bf16_f32 v155, v10, v11
	s_nop 1
	v_permlane16_swap_b32_e32 v152, v154
	v_permlane16_swap_b32_e32 v153, v155
	v_lshl_add_u64 v[158:159], v[18:19], 0, v[156:157]
	global_store_dwordx4 v[158:159], v[152:155], off
	s_nop 1
	s_cbranch_vccnz .LBB0_1533
	v_pk_mul_f32 v[20:21], v[6:7], v[6:7]
	v_pk_mul_f32 v[22:23], v[4:5], v[4:5]
	v_mov_b64_e32 v[24:25], s[40:41]
	v_pk_fma_f32 v[20:21], v[20:21], s[38:39], v[24:25] op_sel_hi:[1,0,0]
	v_pk_fma_f32 v[22:23], v[22:23], s[38:39], v[24:25] op_sel_hi:[1,0,0]
	v_pk_mul_f32 v[20:21], v[6:7], v[20:21]
	v_pk_mul_f32 v[22:23], v[4:5], v[22:23]
	v_exp_f32_e32 v20, v20
	v_exp_f32_e32 v22, v22
	v_exp_f32_e32 v21, v21
	v_exp_f32_e32 v23, v23
	v_pk_add_f32 v[20:21], v[20:21], 1.0 op_sel_hi:[1,0]
	v_pk_add_f32 v[22:23], v[22:23], 1.0 op_sel_hi:[1,0]
	v_rcp_f32_e32 v20, v20
	v_rcp_f32_e32 v22, v22
	v_rcp_f32_e32 v21, v21
	v_rcp_f32_e32 v23, v23
	v_pk_mul_f32 v[6:7], v[6:7], v[20:21]
	v_pk_mul_f32 v[4:5], v[4:5], v[22:23]
.LBB0_1533:
	s_and_b64 vcc, exec, s[0:1]
	v_cvt_pk_bf16_f32 v152, v4, v5
	v_cvt_pk_bf16_f32 v153, v6, v7
	s_cbranch_vccnz .LBB0_1535
	v_pk_mul_f32 v[20:21], v[2:3], v[2:3]
	v_pk_mul_f32 v[22:23], v[0:1], v[0:1]
	v_mov_b64_e32 v[24:25], s[40:41]
	v_pk_fma_f32 v[20:21], v[20:21], s[38:39], v[24:25] op_sel_hi:[1,0,0]
	v_pk_fma_f32 v[22:23], v[22:23], s[38:39], v[24:25] op_sel_hi:[1,0,0]
	v_pk_mul_f32 v[20:21], v[2:3], v[20:21]
	v_pk_mul_f32 v[22:23], v[0:1], v[22:23]
	v_exp_f32_e32 v20, v20
	v_exp_f32_e32 v22, v22
	v_exp_f32_e32 v21, v21
	v_exp_f32_e32 v23, v23
	v_pk_add_f32 v[20:21], v[20:21], 1.0 op_sel_hi:[1,0]
	v_pk_add_f32 v[22:23], v[22:23], 1.0 op_sel_hi:[1,0]
	v_rcp_f32_e32 v20, v20
	v_rcp_f32_e32 v22, v22
	v_rcp_f32_e32 v21, v21
	v_rcp_f32_e32 v23, v23
	v_pk_mul_f32 v[2:3], v[2:3], v[20:21]
	v_pk_mul_f32 v[0:1], v[0:1], v[22:23]
.LBB0_1535:
	s_and_b64 vcc, exec, s[4:5]
	v_cvt_pk_bf16_f32 v154, v0, v1
	v_cvt_pk_bf16_f32 v155, v2, v3
	s_nop 1
	v_permlane16_swap_b32_e32 v152, v154
	v_permlane16_swap_b32_e32 v153, v155
	v_lshl_add_u64 v[158:159], v[18:19], 0, v[156:157]
	global_store_dwordx4 v[158:159], v[152:155], off offset:256
	s_nop 1
	s_cbranch_vccnz .LBB0_1428
	v_mov_b32_e32 v18, v14
	v_mov_b32_e32 v19, v12
	v_mov_b32_e32 v20, v15
	v_mov_b32_e32 v21, v12
	v_pk_add_f32 v[22:23], v[18:19], v[20:21]
	v_pk_mul_f32 v[18:19], v[18:19], v[20:21]
	v_mul_f32_e32 v21, v10, v10
	v_mov_b32_e32 v23, v19
	v_pk_add_f32 v[18:19], v[12:13], v[12:13] op_sel:[1,0]
	v_pk_mul_f32 v[12:13], v[12:13], v[12:13]
	v_mov_b32_e32 v20, v10
	v_mov_b32_e32 v19, v13
	v_pk_add_f32 v[12:13], v[18:19], v[22:23]
	v_mul_f32_e32 v18, v14, v14
	v_pk_fma_f32 v[14:15], v[14:15], v[14:15], v[18:19] op_sel_hi:[1,1,0]
	v_mul_f32_e32 v19, v9, v9
	v_mov_b32_e32 v14, v65
	v_pk_add_f32 v[12:13], v[12:13], v[14:15]
	v_mul_f32_e32 v15, v8, v8
	v_mul_f32_e32 v23, v11, v11
	v_mov_b32_e32 v14, v8
	v_mov_b32_e32 v18, v9
	v_mov_b32_e32 v22, v11
	v_pk_add_f32 v[8:9], v[14:15], v[18:19]
	v_pk_add_f32 v[10:11], v[20:21], v[22:23]
	v_mul_f32_e32 v15, v6, v6
	v_pk_add_f32 v[8:9], v[8:9], v[10:11]
	v_mul_f32_e32 v11, v4, v4
	v_pk_add_f32 v[8:9], v[12:13], v[8:9]
	v_mul_f32_e32 v13, v5, v5
	v_mul_f32_e32 v19, v7, v7
	v_mov_b32_e32 v10, v4
	v_mov_b32_e32 v12, v5
	v_mov_b32_e32 v14, v6
	v_mov_b32_e32 v18, v7
	v_pk_add_f32 v[4:5], v[10:11], v[12:13]
	v_pk_add_f32 v[6:7], v[14:15], v[18:19]
	v_cmp_lt_i32_e32 vcc, v206, v204
	v_pk_add_f32 v[4:5], v[4:5], v[6:7]
	v_mul_f32_e32 v7, v0, v0
	v_cndmask_b32_e32 v6, v203, v206, vcc
	v_pk_add_f32 v[4:5], v[8:9], v[4:5]
	v_mul_f32_e32 v9, v1, v1
	v_mul_f32_e32 v11, v2, v2
	v_mul_f32_e32 v13, v3, v3
	v_lshlrev_b32_e32 v14, 2, v6
	v_mov_b32_e32 v6, v0
	v_mov_b32_e32 v8, v1
	v_mov_b32_e32 v10, v2
	v_mov_b32_e32 v12, v3
	v_pk_add_f32 v[0:1], v[6:7], v[8:9]
	v_pk_add_f32 v[2:3], v[10:11], v[12:13]
	v_cmp_lt_i32_e32 vcc, v205, v204
	v_pk_add_f32 v[0:1], v[0:1], v[2:3]
	s_nop 0
	v_pk_add_f32 v[0:1], v[4:5], v[0:1]
	ds_bpermute_b32 v2, v14, v0
	ds_bpermute_b32 v3, v14, v1
	v_cndmask_b32_e32 v4, v203, v205, vcc
	v_lshlrev_b32_e32 v4, 2, v4
	s_waitcnt lgkmcnt(0)
	v_pk_add_f32 v[0:1], v[0:1], v[2:3]
	ds_bpermute_b32 v2, v4, v0
	ds_bpermute_b32 v3, v4, v1
	s_and_saveexec_b64 s[0:1], s[6:7]
	s_cbranch_execz .LBB0_1427
	v_readlane_b32 s2, v249, 5
	v_lshlrev_b64 v[4:5], 7, v[16:17]
	v_readlane_b32 s3, v249, 6
	s_waitcnt lgkmcnt(0)
	v_pk_add_f32 v[0:1], v[0:1], v[2:3]
	v_lshl_add_u64 v[4:5], s[2:3], 0, v[4:5]
	v_lshl_add_u64 v[4:5], s[94:95], 3, v[4:5]
	global_store_dwordx2 v[4:5], v[0:1], off
	s_branch .LBB0_1427
